# speedup vs baseline: 1.0310x; 1.0310x over previous
; #define WAIT_V(n) asm volatile("s_waitcnt vmcnt(" #n ")" ::: "memory")
; #define BAR __builtin_amdgcn_s_barrier()
; #define TILE_COORDS(wg, pm_, pn_) do { constexpr int WGM = 8; const int nig = WGM * nN, gid = (wg) / nig, fm = gid * WGM, gsz = min(nM - fm, WGM); \
;     pm_ = fm + (((wg) % nig) % gsz); pn_ = ((wg) % nig) / gsz; } while (0)
; #define PROLOGUE4(br_, bc_) do { STAGE(SB(0, 0), Bt, bc_, 0); STAGE(SA(0, 0), A, br_, 0); \
;     STAGE(SB(0, 1), Bt, (bc_) + HALF, 0); STAGE(SA(0, 1), A, (br_) + HALF, 0); } while (0)
; template <int EPI> ...
;     ...
;   if (vb < nwg) { int pm0, pn0; TILE_COORDS(vb, pm0, pn0); PROLOGUE4(pm0 * BM, pn0 * BM); }
;   for (int tile0 = 0; tile0 < nwg; tile0 += gridDim.x) {
;     const int wgid = tile0 + vb;
;     if (wgid >= nwg) break;
;     int pm, pn; TILE_COORDS(wgid, pm, pn);
;     const int brow = pm * BM, bcol = pn * BM;
;     f32x4 acc[2][2][4][2] = {};
;     bf16x8 At[4][2], B0[2][2], B1[2][2];
;     if (wr == 1) BAR;
;     WAIT_V(0); BAR;
;     STAGE(SB(1, 0), Bt, bcol, 1); STAGE(SA(1, 0), A, brow, 1); STAGE(SB(1, 1), Bt, bcol + HALF, 1);
;     WAIT_V(6); BAR;
.LBB0_113:
	s_or_b64 exec, exec, s[14:15]
	s_mul_hi_i32 s14, s21, 0x4bda12f7
	s_lshr_b32 s15, s14, 31
	s_ashr_i32 s14, s14, 7
	s_add_i32 s14, s14, s15
	s_lshl_b32 s31, s14, 3
	s_mulk_i32 s14, 0x1b0
	s_sub_i32 s30, s21, s14
	s_sext_i32_i16 s14, s30
	s_bfe_u32 s14, s14, 0x3001c
	s_add_i32 s14, s30, s14
	s_sext_i32_i16 s15, s14
	s_and_b32 s14, s14, 0xfff8
	s_ashr_i32 s20, s15, 3
	s_sub_i32 s14, s30, s14
	s_lshl_b32 s18, s20, 1
	s_sext_i32_i16 s14, s14
	s_ashr_i32 s19, s18, 31
	s_add_i32 s31, s31, s14
	s_lshl_b64 s[14:15], s[18:19], 20
	s_add_u32 s34, s22, s14
	s_addc_u32 s35, s23, s15
	s_add_u32 s14, s34, 0x4000
	s_addc_u32 s15, s35, 0
	v_readfirstlane_b32 s19, v169
	s_waitcnt vmcnt(0)
	s_barrier
	s_mov_b32 m0, s19
	v_lshl_add_u64 v[2:3], s[14:15], 0, v[130:131]
	global_load_lds_dwordx4 v[2:3], off
	v_lshl_add_u64 v[2:3], s[14:15], 0, v[132:133]
	v_readfirstlane_b32 s14, v170
	s_mov_b32 m0, s14
	s_lshl_b32 s14, s31, 1
	s_ashr_i32 s15, s14, 31
	s_lshl_b64 s[38:39], s[14:15], 20
	s_add_u32 s15, s16, s38
	s_addc_u32 s38, s17, s39
	s_add_u32 s82, s15, 0x4000
	s_addc_u32 s83, s38, 0
	v_readfirstlane_b32 s19, v157
	global_load_lds_dwordx4 v[2:3], off
	s_mov_b32 m0, s19
	v_lshl_add_u64 v[2:3], s[82:83], 0, v[130:131]
	v_readfirstlane_b32 s19, v158
	s_or_b32 s18, s18, 1
	global_load_lds_dwordx4 v[2:3], off
	s_mov_b32 m0, s19
	s_ashr_i32 s19, s18, 31
	s_lshl_b64 s[18:19], s[18:19], 20
	s_add_u32 s18, s22, s18
	s_addc_u32 s19, s23, s19
	s_add_u32 s18, s18, 0x4000
	v_lshl_add_u64 v[2:3], s[82:83], 0, v[132:133]
	s_addc_u32 s19, s19, 0
	v_readfirstlane_b32 s39, v171
	global_load_lds_dwordx4 v[2:3], off
	s_mov_b32 m0, s39
	v_lshl_add_u64 v[2:3], s[18:19], 0, v[130:131]
	global_load_lds_dwordx4 v[2:3], off
	v_lshl_add_u64 v[2:3], s[18:19], 0, v[132:133]
	v_readfirstlane_b32 s18, v172
	s_mov_b32 m0, s18
	s_mov_b32 s39, -2
	global_load_lds_dwordx4 v[2:3], off
	s_waitcnt vmcnt(6)
	v_mov_b32_e32 v2, 0
	s_mov_b64 s[18:19], 0
	v_mov_b32_e32 v3, v2
	v_mov_b32_e32 v4, v2
	v_mov_b32_e32 v5, v2
	v_mov_b32_e32 v6, v2
	v_mov_b32_e32 v7, v2
	v_mov_b32_e32 v8, v2
	v_mov_b32_e32 v9, v2
	v_mov_b32_e32 v10, v2
	v_mov_b32_e32 v11, v2
	s_waitcnt lgkmcnt(0)
	v_mov_b32_e32 v12, v2
	v_mov_b32_e32 v13, v2
	v_mov_b32_e32 v14, v2
	v_mov_b32_e32 v15, v2
	v_mov_b32_e32 v16, v2
	v_mov_b32_e32 v17, v2
	v_mov_b32_e32 v18, v2
	v_mov_b32_e32 v19, v2
	v_mov_b32_e32 v20, v2
	v_mov_b32_e32 v21, v2
	v_mov_b32_e32 v22, v2
	v_mov_b32_e32 v23, v2
	v_mov_b32_e32 v24, v2
	v_mov_b32_e32 v25, v2
	v_mov_b32_e32 v26, v2
	v_mov_b32_e32 v27, v2
	v_mov_b32_e32 v28, v2
	v_mov_b32_e32 v29, v2
	v_mov_b32_e32 v30, v2
	v_mov_b32_e32 v31, v2
	v_mov_b32_e32 v32, v2
	v_mov_b32_e32 v33, v2
	v_mov_b32_e32 v34, v2
	v_mov_b32_e32 v35, v2
	v_mov_b32_e32 v36, v2
	v_mov_b32_e32 v37, v2
	v_mov_b32_e32 v38, v2
	v_mov_b32_e32 v39, v2
	v_mov_b32_e32 v40, v2
	v_mov_b32_e32 v41, v2
	v_mov_b32_e32 v42, v2
	v_mov_b32_e32 v43, v2
	v_mov_b32_e32 v44, v2
	v_mov_b32_e32 v45, v2
	v_mov_b32_e32 v46, v2
	v_mov_b32_e32 v47, v2
	v_mov_b32_e32 v48, v2
	v_mov_b32_e32 v49, v2
	v_mov_b32_e32 v50, v2
	v_mov_b32_e32 v51, v2
	v_mov_b32_e32 v52, v2
	v_mov_b32_e32 v53, v2
	v_mov_b32_e32 v54, v2
	v_mov_b32_e32 v55, v2
	v_mov_b32_e32 v56, v2
	v_mov_b32_e32 v57, v2
	v_mov_b32_e32 v70, v2
	v_mov_b32_e32 v71, v2
	v_mov_b32_e32 v72, v2
	v_mov_b32_e32 v73, v2
	v_mov_b32_e32 v86, v2
	v_mov_b32_e32 v87, v2
	v_mov_b32_e32 v88, v2
	v_mov_b32_e32 v89, v2
	v_mov_b32_e32 v98, v2
	v_mov_b32_e32 v99, v2
	v_mov_b32_e32 v100, v2
	v_mov_b32_e32 v101, v2
	v_mov_b32_e32 v102, v2
	v_mov_b32_e32 v103, v2
	v_mov_b32_e32 v104, v2
	v_mov_b32_e32 v105, v2
	v_mov_b32_e32 v106, v2
	v_mov_b32_e32 v107, v2
	v_mov_b32_e32 v108, v2
	v_mov_b32_e32 v109, v2
	v_mov_b32_e32 v110, v2
	v_mov_b32_e32 v111, v2
	v_mov_b32_e32 v112, v2
	v_mov_b32_e32 v113, v2
	v_mov_b32_e32 v114, v2
	v_mov_b32_e32 v115, v2
	v_mov_b32_e32 v116, v2
	v_mov_b32_e32 v117, v2
	v_mov_b32_e32 v118, v2
	v_mov_b32_e32 v119, v2
	v_mov_b32_e32 v120, v2
	v_mov_b32_e32 v121, v2
	v_mov_b32_e32 v122, v2
	v_mov_b32_e32 v123, v2
	v_mov_b32_e32 v124, v2
	v_mov_b32_e32 v125, v2
	v_mov_b32_e32 v126, v2
	v_mov_b32_e32 v127, v2
	v_mov_b32_e32 v128, v2
	v_mov_b32_e32 v129, v2
	v_mov_b32_e32 v58, v2
	v_mov_b32_e32 v59, v2
	v_mov_b32_e32 v60, v2
	v_mov_b32_e32 v61, v2
	v_mov_b32_e32 v62, v2
	v_mov_b32_e32 v63, v2
	v_mov_b32_e32 v64, v2
	v_mov_b32_e32 v65, v2
	v_mov_b32_e32 v66, v2
	v_mov_b32_e32 v67, v2
	v_mov_b32_e32 v68, v2
	v_mov_b32_e32 v69, v2
	v_mov_b32_e32 v74, v2
	v_mov_b32_e32 v75, v2
	v_mov_b32_e32 v76, v2
	v_mov_b32_e32 v77, v2
	v_mov_b32_e32 v78, v2
	v_mov_b32_e32 v79, v2
	v_mov_b32_e32 v80, v2
	v_mov_b32_e32 v81, v2
	v_mov_b32_e32 v82, v2
	v_mov_b32_e32 v83, v2
	v_mov_b32_e32 v84, v2
	v_mov_b32_e32 v85, v2
	v_mov_b32_e32 v90, v2
	v_mov_b32_e32 v91, v2
	v_mov_b32_e32 v92, v2
	v_mov_b32_e32 v93, v2
	v_mov_b32_e32 v94, v2
	v_mov_b32_e32 v95, v2
	v_mov_b32_e32 v96, v2
	v_mov_b32_e32 v97, v2
	s_barrier
	v_readfirstlane_b32 s32, v151
	ds_read_b128 v[134:137], v159
	ds_read_b128 v[138:141], v159 offset:1024
	ds_read_b128 v[142:145], v159 offset:2048
	ds_read_b128 v[176:179], v159 offset:3072
; #define LDA(dst, b, h) for (int m = 0; m < 4; ++m) for (int k = 0; k < 2; ++k) \
;     dst[m][k] = *reinterpret_cast<const bf16x8*>((char*)SA(b, h) + lds_byte(wr * 64 + m * 16 + fr, k * 32 + fq * 8))
; #define LDB(dst, b, h) for (int n = 0; n < 2; ++n) for (int k = 0; k < 2; ++k) \
;     dst[n][k] = *reinterpret_cast<const bf16x8*>((char*)SB(b, h) + lds_byte(wc * 32 + n * 16 + fr, k * 32 + fq * 8))
; #define MMA(ai, bj, At, Bt_) do { __builtin_amdgcn_s_setprio(1); \
;     for (int m = 0; m < 4; ++m) for (int n = 0; n < 2; ++n) for (int k = 0; k < 2; ++k) \
;       acc[ai][bj][m][n] = __builtin_amdgcn_mfma_f32_16x16x32_bf16(Bt_[n][k], At[m][k], acc[ai][bj][m][n], 0, 0, 0); \
;     __builtin_amdgcn_s_setprio(0); } while (0)
; #define WAIT_V(n) asm volatile("s_waitcnt vmcnt(" #n ")" ::: "memory")
; #define WAIT_L(n) asm volatile("s_waitcnt lgkmcnt(" #n ")" ::: "memory")
; #define BAR __builtin_amdgcn_s_barrier()
; #define SCHED __builtin_amdgcn_sched_barrier(0)
; template <int EPI> ...
;     ...
;     for (int t = 0; t < nt - 2; t += 2) {
;       LDB(B0, 0, 0); SCHED; LDA(At, 0, 0); STAGE(SA(1, 1), A, brow + HALF, t + 1);
;       WAIT_L(8); BAR; WAIT_L(0); MMA(0, 0, At, B0); BAR; SCHED;
;       LDB(B1, 0, 1); STAGE(SB(0, 0), Bt, bcol, t + 2);
;       BAR; WAIT_L(0); MMA(0, 1, At, B1); BAR;
;       LDA(At, 0, 1); STAGE(SA(0, 0), A, brow, t + 2);
;       BAR; WAIT_L(0); MMA(1, 0, At, B0); BAR; SCHED;
;       STAGE(SB(0, 1), Bt, bcol + HALF, t + 2);
;       WAIT_V(6); BAR; MMA(1, 1, At, B1); BAR;
.LBB0_114:
	s_add_u32 s55, s15, s18
	s_addc_u32 s81, s38, s19
	s_add_u32 s82, s55, 0x104000
	s_addc_u32 s83, s81, 0
	ds_read_b128 v[180:183], v160
	ds_read_b128 v[184:187], v160 offset:1024
	ds_read_b128 v[200:203], v161
	ds_read_b128 v[204:207], v161 offset:1024
	ds_read_b128 v[208:211], v162
	ds_read_b128 v[212:215], v162 offset:1024
	ds_read_b128 v[216:219], v163
	ds_read_b128 v[220:223], v163 offset:1024
	s_add_u32 m0, s32, 0xc000
	s_nop 0
	global_load_lds_dwordx4 v130, s[82:83]
	s_add_u32 m0, s32, 0xe000
	s_nop 0
	global_load_lds_dwordx4 v132, s[82:83]
	s_waitcnt lgkmcnt(8)
	s_barrier
	s_waitcnt lgkmcnt(0)
	s_setprio 1
	s_waitcnt lgkmcnt(0)
	v_mfma_f32_16x16x32_bf16 v[126:129], v[134:137], v[180:183], v[126:129]
	v_mfma_f32_16x16x32_bf16 v[122:125], v[142:145], v[180:183], v[122:125]
	v_mfma_f32_16x16x32_bf16 v[118:121], v[134:137], v[200:203], v[118:121]
	v_mfma_f32_16x16x32_bf16 v[114:117], v[142:145], v[200:203], v[114:117]
	v_mfma_f32_16x16x32_bf16 v[110:113], v[134:137], v[208:211], v[110:113]
	v_mfma_f32_16x16x32_bf16 v[106:109], v[142:145], v[208:211], v[106:109]
	v_mfma_f32_16x16x32_bf16 v[102:105], v[134:137], v[216:219], v[102:105]
	v_mfma_f32_16x16x32_bf16 v[98:101], v[142:145], v[216:219], v[98:101]
	v_mfma_f32_16x16x32_bf16 v[126:129], v[138:141], v[184:187], v[126:129]
	v_mfma_f32_16x16x32_bf16 v[122:125], v[176:179], v[184:187], v[122:125]
	v_mfma_f32_16x16x32_bf16 v[118:121], v[138:141], v[204:207], v[118:121]
	v_mfma_f32_16x16x32_bf16 v[114:117], v[176:179], v[204:207], v[114:117]
	v_mfma_f32_16x16x32_bf16 v[110:113], v[138:141], v[212:215], v[110:113]
	v_mfma_f32_16x16x32_bf16 v[106:109], v[176:179], v[212:215], v[106:109]
	v_mfma_f32_16x16x32_bf16 v[102:105], v[138:141], v[220:223], v[102:105]
	v_mfma_f32_16x16x32_bf16 v[98:101], v[176:179], v[220:223], v[98:101]
	s_setprio 0
	s_barrier
	s_add_u32 s82, s34, s18
	s_addc_u32 s83, s35, s19
	s_add_u32 s86, s82, 0x8000
	s_addc_u32 s87, s83, 0
	ds_read_b128 v[224:227], v166
	ds_read_b128 v[228:231], v166 offset:1024
	ds_read_b128 v[232:235], v166 offset:2048
	ds_read_b128 v[236:239], v166 offset:3072
	s_add_u32 m0, s32, 0x10000
	s_nop 0
	global_load_lds_dwordx4 v130, s[86:87]
	s_add_u32 m0, s32, 0x12000
	s_nop 0
	global_load_lds_dwordx4 v132, s[86:87]
	s_barrier
	s_waitcnt lgkmcnt(0)
	s_setprio 1
	s_waitcnt lgkmcnt(0)
	v_mfma_f32_16x16x32_bf16 v[86:89], v[224:227], v[180:183], v[86:89]
	v_mfma_f32_16x16x32_bf16 v[70:73], v[232:235], v[180:183], v[70:73]
	v_mfma_f32_16x16x32_bf16 v[54:57], v[224:227], v[200:203], v[54:57]
	v_mfma_f32_16x16x32_bf16 v[50:53], v[232:235], v[200:203], v[50:53]
	v_mfma_f32_16x16x32_bf16 v[46:49], v[224:227], v[208:211], v[46:49]
	v_mfma_f32_16x16x32_bf16 v[42:45], v[232:235], v[208:211], v[42:45]
	v_mfma_f32_16x16x32_bf16 v[38:41], v[224:227], v[216:219], v[38:41]
	v_mfma_f32_16x16x32_bf16 v[34:37], v[232:235], v[216:219], v[34:37]
	v_mfma_f32_16x16x32_bf16 v[86:89], v[228:231], v[184:187], v[86:89]
	v_mfma_f32_16x16x32_bf16 v[70:73], v[236:239], v[184:187], v[70:73]
	v_mfma_f32_16x16x32_bf16 v[54:57], v[228:231], v[204:207], v[54:57]
	v_mfma_f32_16x16x32_bf16 v[50:53], v[236:239], v[204:207], v[50:53]
	v_mfma_f32_16x16x32_bf16 v[46:49], v[228:231], v[212:215], v[46:49]
	v_mfma_f32_16x16x32_bf16 v[42:45], v[236:239], v[212:215], v[42:45]
	v_mfma_f32_16x16x32_bf16 v[38:41], v[228:231], v[220:223], v[38:41]
	v_mfma_f32_16x16x32_bf16 v[34:37], v[236:239], v[220:223], v[34:37]
	s_setprio 0
	s_add_u32 s86, s55, 0x8000
	s_addc_u32 s87, s81, 0
	s_barrier
	ds_read_b128 v[180:183], v160 offset:16384
	ds_read_b128 v[184:187], v160 offset:17408
	ds_read_b128 v[200:203], v161 offset:16384
	ds_read_b128 v[204:207], v161 offset:17408
	ds_read_b128 v[208:211], v162 offset:16384
	ds_read_b128 v[212:215], v162 offset:17408
	ds_read_b128 v[216:219], v163 offset:16384
	ds_read_b128 v[220:223], v163 offset:17408
	s_add_u32 m0, s32, 0x0
	s_nop 0
	global_load_lds_dwordx4 v130, s[86:87]
	s_add_u32 m0, s32, 0x2000
	s_nop 0
	global_load_lds_dwordx4 v132, s[86:87]
	s_waitcnt vmcnt(10)
	s_barrier
	s_waitcnt lgkmcnt(0)
	s_setprio 1
	s_waitcnt lgkmcnt(0)
	v_mfma_f32_16x16x32_bf16 v[30:33], v[134:137], v[180:183], v[30:33]
	v_mfma_f32_16x16x32_bf16 v[26:29], v[142:145], v[180:183], v[26:29]
	v_mfma_f32_16x16x32_bf16 v[22:25], v[134:137], v[200:203], v[22:25]
	v_mfma_f32_16x16x32_bf16 v[18:21], v[142:145], v[200:203], v[18:21]
	v_mfma_f32_16x16x32_bf16 v[14:17], v[134:137], v[208:211], v[14:17]
	v_mfma_f32_16x16x32_bf16 v[10:13], v[142:145], v[208:211], v[10:13]
	v_mfma_f32_16x16x32_bf16 v[6:9], v[134:137], v[216:219], v[6:9]
	v_mfma_f32_16x16x32_bf16 v[2:5], v[142:145], v[216:219], v[2:5]
	v_mfma_f32_16x16x32_bf16 v[30:33], v[138:141], v[184:187], v[30:33]
	v_mfma_f32_16x16x32_bf16 v[26:29], v[176:179], v[184:187], v[26:29]
	v_mfma_f32_16x16x32_bf16 v[22:25], v[138:141], v[204:207], v[22:25]
	v_mfma_f32_16x16x32_bf16 v[18:21], v[176:179], v[204:207], v[18:21]
	v_mfma_f32_16x16x32_bf16 v[14:17], v[138:141], v[212:215], v[14:17]
	v_mfma_f32_16x16x32_bf16 v[10:13], v[176:179], v[212:215], v[10:13]
	v_mfma_f32_16x16x32_bf16 v[6:9], v[138:141], v[220:223], v[6:9]
	v_mfma_f32_16x16x32_bf16 v[2:5], v[176:179], v[220:223], v[2:5]
	s_setprio 0
	s_barrier
	ds_read_b128 v[134:137], v167
	ds_read_b128 v[138:141], v167 offset:1024
	ds_read_b128 v[142:145], v167 offset:2048
	ds_read_b128 v[176:179], v167 offset:3072
	s_add_u32 s86, s82, 0x108000
	s_addc_u32 s87, s83, 0
	s_add_u32 m0, s32, 0x14000
	s_nop 0
	global_load_lds_dwordx4 v130, s[86:87]
	s_add_u32 m0, s32, 0x16000
	s_nop 0
	global_load_lds_dwordx4 v132, s[86:87]
	s_waitcnt vmcnt(6)
	s_barrier
; #define LDA(dst, b, h) for (int m = 0; m < 4; ++m) for (int k = 0; k < 2; ++k) \
;     dst[m][k] = *reinterpret_cast<const bf16x8*>((char*)SA(b, h) + lds_byte(wr * 64 + m * 16 + fr, k * 32 + fq * 8))
; #define LDB(dst, b, h) for (int n = 0; n < 2; ++n) for (int k = 0; k < 2; ++k) \
;     dst[n][k] = *reinterpret_cast<const bf16x8*>((char*)SB(b, h) + lds_byte(wc * 32 + n * 16 + fr, k * 32 + fq * 8))
; #define MMA(ai, bj, At, Bt_) do { __builtin_amdgcn_s_setprio(1); \
;     for (int m = 0; m < 4; ++m) for (int n = 0; n < 2; ++n) for (int k = 0; k < 2; ++k) \
;       acc[ai][bj][m][n] = __builtin_amdgcn_mfma_f32_16x16x32_bf16(Bt_[n][k], At[m][k], acc[ai][bj][m][n], 0, 0, 0); \
;     __builtin_amdgcn_s_setprio(0); } while (0)
; #define WAIT_V(n) asm volatile("s_waitcnt vmcnt(" #n ")" ::: "memory")
; #define WAIT_L(n) asm volatile("s_waitcnt lgkmcnt(" #n ")" ::: "memory")
; #define BAR __builtin_amdgcn_s_barrier()
; #define SCHED __builtin_amdgcn_sched_barrier(0)
; template <int EPI> ...
;     ...
;       WAIT_V(6); BAR; MMA(1, 1, At, B1); BAR;
;       LDB(B0, 1, 0); SCHED; LDA(At, 1, 0); STAGE(SA(0, 1), A, brow + HALF, t + 2);
;       WAIT_L(8); BAR; WAIT_L(0); MMA(0, 0, At, B0); BAR; SCHED;
;       LDB(B1, 1, 1); STAGE(SB(1, 0), Bt, bcol, t + 3);
;       BAR; WAIT_L(0); MMA(0, 1, At, B1); BAR;
;       LDA(At, 1, 1); STAGE(SA(1, 0), A, brow, t + 3);
;       BAR; WAIT_L(0); MMA(1, 0, At, B0); BAR; SCHED;
;       STAGE(SB(1, 1), Bt, bcol + HALF, t + 3);
;       WAIT_V(6); BAR; MMA(1, 1, At, B1); BAR;
	s_setprio 1
	v_mfma_f32_16x16x32_bf16 v[58:61], v[224:227], v[180:183], v[58:61]
	v_mfma_f32_16x16x32_bf16 v[62:65], v[232:235], v[180:183], v[62:65]
	v_mfma_f32_16x16x32_bf16 v[66:69], v[224:227], v[200:203], v[66:69]
	v_mfma_f32_16x16x32_bf16 v[74:77], v[232:235], v[200:203], v[74:77]
	v_mfma_f32_16x16x32_bf16 v[78:81], v[224:227], v[208:211], v[78:81]
	v_mfma_f32_16x16x32_bf16 v[82:85], v[232:235], v[208:211], v[82:85]
	v_mfma_f32_16x16x32_bf16 v[90:93], v[224:227], v[216:219], v[90:93]
	v_mfma_f32_16x16x32_bf16 v[94:97], v[232:235], v[216:219], v[94:97]
	v_mfma_f32_16x16x32_bf16 v[58:61], v[228:231], v[184:187], v[58:61]
	v_mfma_f32_16x16x32_bf16 v[62:65], v[236:239], v[184:187], v[62:65]
	v_mfma_f32_16x16x32_bf16 v[66:69], v[228:231], v[204:207], v[66:69]
	v_mfma_f32_16x16x32_bf16 v[74:77], v[236:239], v[204:207], v[74:77]
	v_mfma_f32_16x16x32_bf16 v[78:81], v[228:231], v[212:215], v[78:81]
	v_mfma_f32_16x16x32_bf16 v[82:85], v[236:239], v[212:215], v[82:85]
	v_mfma_f32_16x16x32_bf16 v[90:93], v[228:231], v[220:223], v[90:93]
	v_mfma_f32_16x16x32_bf16 v[94:97], v[236:239], v[220:223], v[94:97]
	s_setprio 0
	s_barrier
	s_add_u32 s86, s55, 0x108000
	s_addc_u32 s87, s81, 0
	ds_read_b128 v[180:183], v160 offset:32768
	ds_read_b128 v[184:187], v160 offset:33792
	ds_read_b128 v[200:203], v161 offset:32768
	ds_read_b128 v[204:207], v161 offset:33792
	ds_read_b128 v[208:211], v162 offset:32768
	ds_read_b128 v[212:215], v162 offset:33792
	ds_read_b128 v[216:219], v163 offset:32768
	ds_read_b128 v[220:223], v163 offset:33792
	s_add_u32 m0, s32, 0x4000
	s_nop 0
	global_load_lds_dwordx4 v130, s[86:87]
	s_add_u32 m0, s32, 0x6000
	s_nop 0
	global_load_lds_dwordx4 v132, s[86:87]
	s_waitcnt lgkmcnt(8)
	s_barrier
	s_waitcnt lgkmcnt(0)
	s_setprio 1
	s_waitcnt lgkmcnt(0)
	v_mfma_f32_16x16x32_bf16 v[126:129], v[134:137], v[180:183], v[126:129]
	v_mfma_f32_16x16x32_bf16 v[122:125], v[142:145], v[180:183], v[122:125]
	v_mfma_f32_16x16x32_bf16 v[118:121], v[134:137], v[200:203], v[118:121]
	v_mfma_f32_16x16x32_bf16 v[114:117], v[142:145], v[200:203], v[114:117]
	v_mfma_f32_16x16x32_bf16 v[110:113], v[134:137], v[208:211], v[110:113]
	v_mfma_f32_16x16x32_bf16 v[106:109], v[142:145], v[208:211], v[106:109]
	v_mfma_f32_16x16x32_bf16 v[102:105], v[134:137], v[216:219], v[102:105]
	v_mfma_f32_16x16x32_bf16 v[98:101], v[142:145], v[216:219], v[98:101]
	v_mfma_f32_16x16x32_bf16 v[126:129], v[138:141], v[184:187], v[126:129]
	v_mfma_f32_16x16x32_bf16 v[122:125], v[176:179], v[184:187], v[122:125]
	v_mfma_f32_16x16x32_bf16 v[118:121], v[138:141], v[204:207], v[118:121]
	v_mfma_f32_16x16x32_bf16 v[114:117], v[176:179], v[204:207], v[114:117]
	v_mfma_f32_16x16x32_bf16 v[110:113], v[138:141], v[212:215], v[110:113]
	v_mfma_f32_16x16x32_bf16 v[106:109], v[176:179], v[212:215], v[106:109]
	v_mfma_f32_16x16x32_bf16 v[102:105], v[138:141], v[220:223], v[102:105]
	v_mfma_f32_16x16x32_bf16 v[98:101], v[176:179], v[220:223], v[98:101]
	s_setprio 0
	s_barrier
	s_add_u32 s86, s82, 0xc000
	s_addc_u32 s87, s83, 0
	ds_read_b128 v[224:227], v168
	ds_read_b128 v[228:231], v168 offset:1024
	ds_read_b128 v[232:235], v168 offset:2048
	ds_read_b128 v[236:239], v168 offset:3072
	s_add_u32 m0, s32, 0x18000
	s_nop 0
	global_load_lds_dwordx4 v130, s[86:87]
	s_add_u32 m0, s32, 0x1a000
	s_nop 0
	global_load_lds_dwordx4 v132, s[86:87]
	s_barrier
	s_waitcnt lgkmcnt(0)
	s_setprio 1
	s_waitcnt lgkmcnt(0)
	v_mfma_f32_16x16x32_bf16 v[86:89], v[224:227], v[180:183], v[86:89]
	v_mfma_f32_16x16x32_bf16 v[70:73], v[232:235], v[180:183], v[70:73]
	v_mfma_f32_16x16x32_bf16 v[54:57], v[224:227], v[200:203], v[54:57]
	v_mfma_f32_16x16x32_bf16 v[50:53], v[232:235], v[200:203], v[50:53]
	v_mfma_f32_16x16x32_bf16 v[46:49], v[224:227], v[208:211], v[46:49]
	v_mfma_f32_16x16x32_bf16 v[42:45], v[232:235], v[208:211], v[42:45]
	v_mfma_f32_16x16x32_bf16 v[38:41], v[224:227], v[216:219], v[38:41]
	v_mfma_f32_16x16x32_bf16 v[34:37], v[232:235], v[216:219], v[34:37]
	v_mfma_f32_16x16x32_bf16 v[86:89], v[228:231], v[184:187], v[86:89]
	v_mfma_f32_16x16x32_bf16 v[70:73], v[236:239], v[184:187], v[70:73]
	v_mfma_f32_16x16x32_bf16 v[54:57], v[228:231], v[204:207], v[54:57]
	v_mfma_f32_16x16x32_bf16 v[50:53], v[236:239], v[204:207], v[50:53]
	v_mfma_f32_16x16x32_bf16 v[46:49], v[228:231], v[212:215], v[46:49]
	v_mfma_f32_16x16x32_bf16 v[42:45], v[236:239], v[212:215], v[42:45]
	v_mfma_f32_16x16x32_bf16 v[38:41], v[228:231], v[220:223], v[38:41]
	v_mfma_f32_16x16x32_bf16 v[34:37], v[236:239], v[220:223], v[34:37]
	s_setprio 0
	s_add_u32 s86, s55, 0xc000
	s_addc_u32 s87, s81, 0
	s_barrier
	ds_read_b128 v[180:183], v160 offset:49152
	ds_read_b128 v[184:187], v160 offset:50176
	ds_read_b128 v[200:203], v161 offset:49152
	ds_read_b128 v[204:207], v161 offset:50176
	ds_read_b128 v[208:211], v162 offset:49152
	ds_read_b128 v[212:215], v162 offset:50176
	ds_read_b128 v[216:219], v163 offset:49152
	ds_read_b128 v[220:223], v163 offset:50176
	s_add_u32 m0, s32, 0x8000
	s_nop 0
	global_load_lds_dwordx4 v130, s[86:87]
	s_add_u32 m0, s32, 0xa000
	s_nop 0
	global_load_lds_dwordx4 v132, s[86:87]
	s_waitcnt vmcnt(10)
	s_barrier
; #define LDA(dst, b, h) for (int m = 0; m < 4; ++m) for (int k = 0; k < 2; ++k) \
;     dst[m][k] = *reinterpret_cast<const bf16x8*>((char*)SA(b, h) + lds_byte(wr * 64 + m * 16 + fr, k * 32 + fq * 8))
; #define LDB(dst, b, h) for (int n = 0; n < 2; ++n) for (int k = 0; k < 2; ++k) \
;     dst[n][k] = *reinterpret_cast<const bf16x8*>((char*)SB(b, h) + lds_byte(wc * 32 + n * 16 + fr, k * 32 + fq * 8))
; #define MMA(ai, bj, At, Bt_) do { __builtin_amdgcn_s_setprio(1); \
;     for (int m = 0; m < 4; ++m) for (int n = 0; n < 2; ++n) for (int k = 0; k < 2; ++k) \
;       acc[ai][bj][m][n] = __builtin_amdgcn_mfma_f32_16x16x32_bf16(Bt_[n][k], At[m][k], acc[ai][bj][m][n], 0, 0, 0); \
;     __builtin_amdgcn_s_setprio(0); } while (0)
; #define WAIT_V(n) asm volatile("s_waitcnt vmcnt(" #n ")" ::: "memory")
; #define WAIT_L(n) asm volatile("s_waitcnt lgkmcnt(" #n ")" ::: "memory")
; #define BAR __builtin_amdgcn_s_barrier()
; #define SCHED __builtin_amdgcn_sched_barrier(0)
; template <int EPI> ...
;     ...
;       BAR; WAIT_L(0); MMA(1, 0, At, B0); BAR; SCHED;
;       STAGE(SB(1, 1), Bt, bcol + HALF, t + 3);
;       WAIT_V(6); BAR; MMA(1, 1, At, B1); BAR;
;     }
;     { LDB(B0, 0, 0); LDA(At, 0, 0); STAGE(SA(1, 1), A, brow + HALF, nt - 1);
;       BAR; WAIT_L(0); MMA(0, 0, At, B0); BAR;
;       LDB(B1, 0, 1); BAR; WAIT_L(0); MMA(0, 1, At, B1); BAR;
	s_waitcnt lgkmcnt(0)
	s_setprio 1
	s_waitcnt lgkmcnt(0)
	v_mfma_f32_16x16x32_bf16 v[30:33], v[134:137], v[180:183], v[30:33]
	v_mfma_f32_16x16x32_bf16 v[26:29], v[142:145], v[180:183], v[26:29]
	v_mfma_f32_16x16x32_bf16 v[22:25], v[134:137], v[200:203], v[22:25]
	v_mfma_f32_16x16x32_bf16 v[18:21], v[142:145], v[200:203], v[18:21]
	v_mfma_f32_16x16x32_bf16 v[14:17], v[134:137], v[208:211], v[14:17]
	v_mfma_f32_16x16x32_bf16 v[10:13], v[142:145], v[208:211], v[10:13]
	v_mfma_f32_16x16x32_bf16 v[6:9], v[134:137], v[216:219], v[6:9]
	v_mfma_f32_16x16x32_bf16 v[2:5], v[142:145], v[216:219], v[2:5]
	v_mfma_f32_16x16x32_bf16 v[30:33], v[138:141], v[184:187], v[30:33]
	v_mfma_f32_16x16x32_bf16 v[26:29], v[176:179], v[184:187], v[26:29]
	v_mfma_f32_16x16x32_bf16 v[22:25], v[138:141], v[204:207], v[22:25]
	v_mfma_f32_16x16x32_bf16 v[18:21], v[176:179], v[204:207], v[18:21]
	v_mfma_f32_16x16x32_bf16 v[14:17], v[138:141], v[212:215], v[14:17]
	v_mfma_f32_16x16x32_bf16 v[10:13], v[176:179], v[212:215], v[10:13]
	v_mfma_f32_16x16x32_bf16 v[6:9], v[138:141], v[220:223], v[6:9]
	v_mfma_f32_16x16x32_bf16 v[2:5], v[176:179], v[220:223], v[2:5]
	s_setprio 0
	s_barrier
	ds_read_b128 v[134:137], v159
	ds_read_b128 v[138:141], v159 offset:1024
	ds_read_b128 v[142:145], v159 offset:2048
	ds_read_b128 v[176:179], v159 offset:3072
	s_add_u32 s82, s82, 0x10c000
	s_addc_u32 s83, s83, 0
	s_add_u32 m0, s32, 0x1c000
	s_nop 0
	global_load_lds_dwordx4 v130, s[82:83]
	s_add_u32 m0, s32, 0x1e000
	s_nop 0
	global_load_lds_dwordx4 v132, s[82:83]
	s_waitcnt vmcnt(6)
	s_barrier
	s_setprio 1
	v_mfma_f32_16x16x32_bf16 v[58:61], v[224:227], v[180:183], v[58:61]
	v_mfma_f32_16x16x32_bf16 v[62:65], v[232:235], v[180:183], v[62:65]
	v_mfma_f32_16x16x32_bf16 v[66:69], v[224:227], v[200:203], v[66:69]
	v_mfma_f32_16x16x32_bf16 v[74:77], v[232:235], v[200:203], v[74:77]
	v_mfma_f32_16x16x32_bf16 v[78:81], v[224:227], v[208:211], v[78:81]
	v_mfma_f32_16x16x32_bf16 v[82:85], v[232:235], v[208:211], v[82:85]
	v_mfma_f32_16x16x32_bf16 v[90:93], v[224:227], v[216:219], v[90:93]
	v_mfma_f32_16x16x32_bf16 v[94:97], v[232:235], v[216:219], v[94:97]
	v_mfma_f32_16x16x32_bf16 v[58:61], v[228:231], v[184:187], v[58:61]
	v_mfma_f32_16x16x32_bf16 v[62:65], v[236:239], v[184:187], v[62:65]
	v_mfma_f32_16x16x32_bf16 v[66:69], v[228:231], v[204:207], v[66:69]
	v_mfma_f32_16x16x32_bf16 v[74:77], v[236:239], v[204:207], v[74:77]
	v_mfma_f32_16x16x32_bf16 v[78:81], v[228:231], v[212:215], v[78:81]
	v_mfma_f32_16x16x32_bf16 v[82:85], v[236:239], v[212:215], v[82:85]
	v_mfma_f32_16x16x32_bf16 v[90:93], v[228:231], v[220:223], v[90:93]
	v_mfma_f32_16x16x32_bf16 v[94:97], v[236:239], v[220:223], v[94:97]
	s_setprio 0
	s_add_i32 s39, s39, 2
	s_add_u32 s18, s18, 0x8000
	s_addc_u32 s19, s19, 0
	s_cmp_lt_u32 s39, 60
	s_barrier
	s_cbranch_scc1 .LBB0_114
	s_or_b32 s14, s14, 1
	s_ashr_i32 s15, s14, 31
	s_lshl_b64 s[14:15], s[14:15], 20
	s_add_u32 s14, s16, s14
	s_addc_u32 s15, s17, s15
	s_add_u32 s14, s14, 0xfc000
	s_addc_u32 s15, s15, 0
	v_readfirstlane_b32 s18, v164
	ds_read_b128 v[134:137], v159
	ds_read_b128 v[138:141], v159 offset:1024
	ds_read_b128 v[142:145], v159 offset:2048
	ds_read_b128 v[176:179], v159 offset:3072
	ds_read_b128 v[180:183], v160
	ds_read_b128 v[184:187], v160 offset:1024
	ds_read_b128 v[200:203], v161
	ds_read_b128 v[204:207], v161 offset:1024
	ds_read_b128 v[208:211], v162
	ds_read_b128 v[212:215], v162 offset:1024
	ds_read_b128 v[216:219], v163
	ds_read_b128 v[220:223], v163 offset:1024
	s_mov_b32 m0, s18
	v_lshl_add_u64 v[146:147], s[14:15], 0, v[130:131]
	global_load_lds_dwordx4 v[146:147], off
	v_lshl_add_u64 v[146:147], s[14:15], 0, v[132:133]
	v_readfirstlane_b32 s14, v165
	s_mov_b32 m0, s14
	s_nop 0
	global_load_lds_dwordx4 v[146:147], off
	s_barrier
	s_waitcnt lgkmcnt(0)
	s_setprio 1
	s_waitcnt lgkmcnt(0)
	v_mfma_f32_16x16x32_bf16 v[126:129], v[134:137], v[180:183], v[126:129]
	v_mfma_f32_16x16x32_bf16 v[122:125], v[142:145], v[180:183], v[122:125]
	v_mfma_f32_16x16x32_bf16 v[110:113], v[134:137], v[208:211], v[110:113]
	v_mfma_f32_16x16x32_bf16 v[106:109], v[142:145], v[208:211], v[106:109]
	v_mfma_f32_16x16x32_bf16 v[126:129], v[138:141], v[184:187], v[126:129]
	v_mfma_f32_16x16x32_bf16 v[122:125], v[176:179], v[184:187], v[122:125]
	v_mfma_f32_16x16x32_bf16 v[118:121], v[134:137], v[200:203], v[118:121]
	v_mfma_f32_16x16x32_bf16 v[114:117], v[142:145], v[200:203], v[114:117]
	v_mfma_f32_16x16x32_bf16 v[110:113], v[138:141], v[212:215], v[110:113]
	v_mfma_f32_16x16x32_bf16 v[106:109], v[176:179], v[212:215], v[106:109]
	v_mfma_f32_16x16x32_bf16 v[102:105], v[134:137], v[216:219], v[102:105]
	v_mfma_f32_16x16x32_bf16 v[98:101], v[142:145], v[216:219], v[98:101]
	v_mfma_f32_16x16x32_bf16 v[224:227], v[138:141], v[204:207], v[118:121]
	v_mfma_f32_16x16x32_bf16 v[228:231], v[176:179], v[204:207], v[114:117]
	v_mfma_f32_16x16x32_bf16 v[232:235], v[138:141], v[220:223], v[102:105]
	v_mfma_f32_16x16x32_bf16 v[236:239], v[176:179], v[220:223], v[98:101]
	s_setprio 0
	s_barrier
	s_nop 1
	ds_read_b128 v[98:101], v166
	ds_read_b128 v[102:105], v166 offset:1024
	ds_read_b128 v[114:117], v166 offset:2048
	ds_read_b128 v[118:121], v166 offset:3072
	s_barrier
; #define LDA(dst, b, h) for (int m = 0; m < 4; ++m) for (int k = 0; k < 2; ++k) \
;     dst[m][k] = *reinterpret_cast<const bf16x8*>((char*)SA(b, h) + lds_byte(wr * 64 + m * 16 + fr, k * 32 + fq * 8))
; #define LDB(dst, b, h) for (int n = 0; n < 2; ++n) for (int k = 0; k < 2; ++k) \
;     dst[n][k] = *reinterpret_cast<const bf16x8*>((char*)SB(b, h) + lds_byte(wc * 32 + n * 16 + fr, k * 32 + fq * 8))
; #define MMA(ai, bj, At, Bt_) do { __builtin_amdgcn_s_setprio(1); \
;     for (int m = 0; m < 4; ++m) for (int n = 0; n < 2; ++n) for (int k = 0; k < 2; ++k) \
;       acc[ai][bj][m][n] = __builtin_amdgcn_mfma_f32_16x16x32_bf16(Bt_[n][k], At[m][k], acc[ai][bj][m][n], 0, 0, 0); \
;     __builtin_amdgcn_s_setprio(0); } while (0)
; #define WAIT_V(n) asm volatile("s_waitcnt vmcnt(" #n ")" ::: "memory")
; #define WAIT_L(n) asm volatile("s_waitcnt lgkmcnt(" #n ")" ::: "memory")
; #define BAR __builtin_amdgcn_s_barrier()
; template <int EPI> ...
;     ...
;       LDB(B1, 0, 1); BAR; WAIT_L(0); MMA(0, 1, At, B1); BAR;
;       LDA(At, 0, 1); WAIT_V(4); BAR; WAIT_L(0); MMA(1, 0, At, B0); MMA(1, 1, At, B1); BAR; }
;     { LDB(B0, 1, 0); LDA(At, 1, 0); WAIT_V(2); BAR; WAIT_L(0); MMA(0, 0, At, B0); BAR;
	s_waitcnt lgkmcnt(0)
	s_setprio 1
	s_waitcnt lgkmcnt(0)
	v_mfma_f32_16x16x32_bf16 v[70:73], v[114:117], v[180:183], v[70:73]
	v_mfma_f32_16x16x32_bf16 v[46:49], v[98:101], v[208:211], v[46:49]
	v_mfma_f32_16x16x32_bf16 v[42:45], v[114:117], v[208:211], v[42:45]
	v_mfma_f32_16x16x32_bf16 v[38:41], v[98:101], v[216:219], v[38:41]
	v_mfma_f32_16x16x32_bf16 v[34:37], v[114:117], v[216:219], v[34:37]
	v_mfma_f32_16x16x32_bf16 v[86:89], v[98:101], v[180:183], v[86:89]
	v_mfma_f32_16x16x32_bf16 v[70:73], v[118:121], v[184:187], v[70:73]
	v_mfma_f32_16x16x32_bf16 v[54:57], v[98:101], v[200:203], v[54:57]
	v_mfma_f32_16x16x32_bf16 v[50:53], v[114:117], v[200:203], v[50:53]
	v_mfma_f32_16x16x32_bf16 v[46:49], v[102:105], v[212:215], v[46:49]
	v_mfma_f32_16x16x32_bf16 v[42:45], v[118:121], v[212:215], v[42:45]
	v_mfma_f32_16x16x32_bf16 v[38:41], v[102:105], v[220:223], v[38:41]
	v_mfma_f32_16x16x32_bf16 v[34:37], v[118:121], v[220:223], v[34:37]
	v_mfma_f32_16x16x32_bf16 v[240:243], v[102:105], v[184:187], v[86:89]
	v_mfma_f32_16x16x32_bf16 v[180:183], v[102:105], v[204:207], v[54:57]
	v_mfma_f32_16x16x32_bf16 v[184:187], v[118:121], v[204:207], v[50:53]
	s_setprio 0
	s_barrier
	s_nop 0
	ds_read_b128 v[50:53], v160 offset:16384
	ds_read_b128 v[54:57], v160 offset:17408
	ds_read_b128 v[86:89], v161 offset:16384
	ds_read_b128 v[200:203], v161 offset:17408
	ds_read_b128 v[204:207], v162 offset:16384
	ds_read_b128 v[208:211], v162 offset:17408
	ds_read_b128 v[212:215], v163 offset:16384
	ds_read_b128 v[216:219], v163 offset:17408
	s_waitcnt vmcnt(4)
	s_barrier
	s_waitcnt lgkmcnt(0)
	s_setprio 1
	s_waitcnt lgkmcnt(0)
	v_mfma_f32_16x16x32_bf16 v[30:33], v[134:137], v[50:53], v[30:33]
	v_mfma_f32_16x16x32_bf16 v[26:29], v[142:145], v[50:53], v[26:29]
	v_mfma_f32_16x16x32_bf16 v[22:25], v[134:137], v[86:89], v[22:25]
	v_mfma_f32_16x16x32_bf16 v[18:21], v[142:145], v[86:89], v[18:21]
	v_mfma_f32_16x16x32_bf16 v[14:17], v[134:137], v[204:207], v[14:17]
	v_mfma_f32_16x16x32_bf16 v[10:13], v[142:145], v[204:207], v[10:13]
	v_mfma_f32_16x16x32_bf16 v[6:9], v[134:137], v[212:215], v[6:9]
	v_mfma_f32_16x16x32_bf16 v[2:5], v[142:145], v[212:215], v[2:5]
	v_mfma_f32_16x16x32_bf16 v[30:33], v[138:141], v[54:57], v[30:33]
	v_mfma_f32_16x16x32_bf16 v[26:29], v[176:179], v[54:57], v[26:29]
	v_mfma_f32_16x16x32_bf16 v[22:25], v[138:141], v[200:203], v[22:25]
	v_mfma_f32_16x16x32_bf16 v[18:21], v[176:179], v[200:203], v[18:21]
	v_mfma_f32_16x16x32_bf16 v[14:17], v[138:141], v[208:211], v[14:17]
	v_mfma_f32_16x16x32_bf16 v[10:13], v[176:179], v[208:211], v[10:13]
	v_mfma_f32_16x16x32_bf16 v[6:9], v[138:141], v[216:219], v[6:9]
	v_mfma_f32_16x16x32_bf16 v[2:5], v[176:179], v[216:219], v[2:5]
	s_setprio 0
	s_setprio 1
	v_mfma_f32_16x16x32_bf16 v[58:61], v[98:101], v[50:53], v[58:61]
	v_mfma_f32_16x16x32_bf16 v[50:53], v[114:117], v[50:53], v[62:65]
	v_mfma_f32_16x16x32_bf16 v[138:141], v[118:121], v[54:57], v[50:53]
	v_mfma_f32_16x16x32_bf16 v[50:53], v[98:101], v[86:89], v[66:69]
	v_mfma_f32_16x16x32_bf16 v[142:145], v[102:105], v[200:203], v[50:53]
	v_mfma_f32_16x16x32_bf16 v[50:53], v[114:117], v[86:89], v[74:77]
	v_mfma_f32_16x16x32_bf16 v[176:179], v[118:121], v[200:203], v[50:53]
	v_mfma_f32_16x16x32_bf16 v[50:53], v[98:101], v[204:207], v[78:81]
	v_mfma_f32_16x16x32_bf16 v[200:203], v[102:105], v[208:211], v[50:53]
	v_mfma_f32_16x16x32_bf16 v[50:53], v[114:117], v[204:207], v[82:85]
	v_mfma_f32_16x16x32_bf16 v[204:207], v[118:121], v[208:211], v[50:53]
	v_mfma_f32_16x16x32_bf16 v[50:53], v[98:101], v[212:215], v[90:93]
	v_mfma_f32_16x16x32_bf16 v[208:211], v[102:105], v[216:219], v[50:53]
	v_mfma_f32_16x16x32_bf16 v[50:53], v[114:117], v[212:215], v[94:97]
	v_mfma_f32_16x16x32_bf16 v[134:137], v[102:105], v[54:57], v[58:61]
	v_mfma_f32_16x16x32_bf16 v[212:215], v[118:121], v[216:219], v[50:53]
	s_setprio 0
	s_barrier
	ds_read_b128 v[74:77], v167
	ds_read_b128 v[216:219], v167 offset:1024
	ds_read_b128 v[220:223], v167 offset:2048
	ds_read_b128 v[244:247], v167 offset:3072
	ds_read_b128 v[58:61], v160 offset:32768
	ds_read_b128 v[62:65], v160 offset:33792
	ds_read_b128 v[66:69], v161 offset:32768
	ds_read_b128 v[78:81], v161 offset:33792
	ds_read_b128 v[94:97], v162 offset:32768
	ds_read_b128 v[248:251], v162 offset:33792
	ds_read_b128 v[188:191], v163 offset:32768
	ds_read_b128 v[146:149], v163 offset:33792
	s_waitcnt vmcnt(2)
	s_barrier
; #define LDA(dst, b, h) for (int m = 0; m < 4; ++m) for (int k = 0; k < 2; ++k) \
;     dst[m][k] = *reinterpret_cast<const bf16x8*>((char*)SA(b, h) + lds_byte(wr * 64 + m * 16 + fr, k * 32 + fq * 8))
; #define LDB(dst, b, h) for (int n = 0; n < 2; ++n) for (int k = 0; k < 2; ++k) \
;     dst[n][k] = *reinterpret_cast<const bf16x8*>((char*)SB(b, h) + lds_byte(wc * 32 + n * 16 + fr, k * 32 + fq * 8))
; #define MMA(ai, bj, At, Bt_) do { __builtin_amdgcn_s_setprio(1); \
;     for (int m = 0; m < 4; ++m) for (int n = 0; n < 2; ++n) for (int k = 0; k < 2; ++k) \
;       acc[ai][bj][m][n] = __builtin_amdgcn_mfma_f32_16x16x32_bf16(Bt_[n][k], At[m][k], acc[ai][bj][m][n], 0, 0, 0); \
;     __builtin_amdgcn_s_setprio(0); } while (0)
; #define WAIT_V(n) asm volatile("s_waitcnt vmcnt(" #n ")" ::: "memory")
; #define WAIT_L(n) asm volatile("s_waitcnt lgkmcnt(" #n ")" ::: "memory")
; #define BAR __builtin_amdgcn_s_barrier()
; template <int EPI> ...
;     ...
;       LDA(At, 0, 1); WAIT_V(4); BAR; WAIT_L(0); MMA(1, 0, At, B0); MMA(1, 1, At, B1); BAR; }
;     { LDB(B0, 1, 0); LDA(At, 1, 0); WAIT_V(2); BAR; WAIT_L(0); MMA(0, 0, At, B0); BAR;
;       LDB(B1, 1, 1); WAIT_V(0); BAR; WAIT_L(0); MMA(0, 1, At, B1); BAR;
;       LDA(At, 1, 1); BAR; WAIT_L(0); MMA(1, 0, At, B0); MMA(1, 1, At, B1); BAR; }
;     if (wr == 0) BAR;
	s_waitcnt lgkmcnt(0)
	s_setprio 1
	s_waitcnt lgkmcnt(0)
	v_mfma_f32_16x16x32_bf16 v[50:53], v[74:77], v[58:61], v[126:129]
	v_mfma_f32_16x16x32_bf16 v[118:121], v[216:219], v[62:65], v[50:53]
	v_mfma_f32_16x16x32_bf16 v[50:53], v[220:223], v[58:61], v[122:125]
	v_mfma_f32_16x16x32_bf16 v[114:117], v[244:247], v[62:65], v[50:53]
	v_mfma_f32_16x16x32_bf16 v[50:53], v[74:77], v[66:69], v[224:227]
	v_mfma_f32_16x16x32_bf16 v[102:105], v[216:219], v[78:81], v[50:53]
	v_mfma_f32_16x16x32_bf16 v[50:53], v[220:223], v[66:69], v[228:231]
	v_mfma_f32_16x16x32_bf16 v[98:101], v[244:247], v[78:81], v[50:53]
	v_mfma_f32_16x16x32_bf16 v[50:53], v[74:77], v[94:97], v[110:113]
	v_mfma_f32_16x16x32_bf16 v[86:89], v[216:219], v[248:251], v[50:53]
	v_mfma_f32_16x16x32_bf16 v[50:53], v[220:223], v[94:97], v[106:109]
	v_mfma_f32_16x16x32_bf16 v[82:85], v[244:247], v[248:251], v[50:53]
	v_mfma_f32_16x16x32_bf16 v[50:53], v[74:77], v[188:191], v[232:235]
	v_mfma_f32_16x16x32_bf16 v[54:57], v[216:219], v[146:149], v[50:53]
	v_mfma_f32_16x16x32_bf16 v[50:53], v[220:223], v[188:191], v[236:239]
	v_mfma_f32_16x16x32_bf16 v[50:53], v[244:247], v[146:149], v[50:53]
	s_setprio 0
	s_barrier
	ds_read_b128 v[224:227], v168
	ds_read_b128 v[228:231], v168 offset:1024
	ds_read_b128 v[232:235], v168 offset:2048
	ds_read_b128 v[236:239], v168 offset:3072
	s_waitcnt vmcnt(0)
	s_barrier
	s_waitcnt lgkmcnt(0)
	s_setprio 1
	s_waitcnt lgkmcnt(0)
	v_mfma_f32_16x16x32_bf16 v[90:93], v[224:227], v[58:61], v[240:243]
	v_mfma_f32_16x16x32_bf16 v[58:61], v[232:235], v[58:61], v[70:73]
	v_mfma_f32_16x16x32_bf16 v[126:129], v[236:239], v[62:65], v[58:61]
	v_mfma_f32_16x16x32_bf16 v[58:61], v[224:227], v[66:69], v[180:183]
	v_mfma_f32_16x16x32_bf16 v[106:109], v[228:231], v[78:81], v[58:61]
	v_mfma_f32_16x16x32_bf16 v[58:61], v[232:235], v[66:69], v[184:187]
	v_mfma_f32_16x16x32_bf16 v[46:49], v[224:227], v[94:97], v[46:49]
	v_mfma_f32_16x16x32_bf16 v[42:45], v[232:235], v[94:97], v[42:45]
	v_mfma_f32_16x16x32_bf16 v[38:41], v[224:227], v[188:191], v[38:41]
	v_mfma_f32_16x16x32_bf16 v[34:37], v[232:235], v[188:191], v[34:37]
	v_mfma_f32_16x16x32_bf16 v[122:125], v[228:231], v[62:65], v[90:93]
	v_mfma_f32_16x16x32_bf16 v[110:113], v[236:239], v[78:81], v[58:61]
	v_mfma_f32_16x16x32_bf16 v[90:93], v[228:231], v[248:251], v[46:49]
	v_mfma_f32_16x16x32_bf16 v[94:97], v[236:239], v[248:251], v[42:45]
	v_mfma_f32_16x16x32_bf16 v[58:61], v[228:231], v[146:149], v[38:41]
	v_mfma_f32_16x16x32_bf16 v[62:65], v[236:239], v[146:149], v[34:37]
	s_setprio 0
	s_barrier
	ds_read_b128 v[38:41], v160 offset:49152
	ds_read_b128 v[42:45], v160 offset:50176
	ds_read_b128 v[146:149], v161 offset:49152
	ds_read_b128 v[180:183], v161 offset:50176
	ds_read_b128 v[184:187], v162 offset:49152
	ds_read_b128 v[188:191], v162 offset:50176
	ds_read_b128 v[240:243], v163 offset:49152
	ds_read_b128 v[248:251], v163 offset:50176
	s_barrier
	s_waitcnt lgkmcnt(0)
	s_setprio 1
	s_waitcnt lgkmcnt(0)
	v_mfma_f32_16x16x32_bf16 v[30:33], v[74:77], v[38:41], v[30:33]
	v_mfma_f32_16x16x32_bf16 v[26:29], v[220:223], v[38:41], v[26:29]
	v_mfma_f32_16x16x32_bf16 v[22:25], v[74:77], v[146:149], v[22:25]
	v_mfma_f32_16x16x32_bf16 v[18:21], v[220:223], v[146:149], v[18:21]
	v_mfma_f32_16x16x32_bf16 v[14:17], v[74:77], v[184:187], v[14:17]
	v_mfma_f32_16x16x32_bf16 v[10:13], v[220:223], v[184:187], v[10:13]
	v_mfma_f32_16x16x32_bf16 v[6:9], v[74:77], v[240:243], v[6:9]
	v_mfma_f32_16x16x32_bf16 v[2:5], v[220:223], v[240:243], v[2:5]
	v_mfma_f32_16x16x32_bf16 v[78:81], v[216:219], v[42:45], v[30:33]
	v_mfma_f32_16x16x32_bf16 v[66:69], v[244:247], v[42:45], v[26:29]
	v_mfma_f32_16x16x32_bf16 v[46:49], v[216:219], v[180:183], v[22:25]
	v_mfma_f32_16x16x32_bf16 v[34:37], v[244:247], v[180:183], v[18:21]
	v_mfma_f32_16x16x32_bf16 v[30:33], v[216:219], v[188:191], v[14:17]
	v_mfma_f32_16x16x32_bf16 v[18:21], v[244:247], v[188:191], v[10:13]
	v_mfma_f32_16x16x32_bf16 v[6:9], v[216:219], v[248:251], v[6:9]
	v_mfma_f32_16x16x32_bf16 v[2:5], v[244:247], v[248:251], v[2:5]
	s_setprio 0
	s_setprio 1
	v_mfma_f32_16x16x32_bf16 v[10:13], v[224:227], v[38:41], v[134:137]
	v_mfma_f32_16x16x32_bf16 v[70:73], v[228:231], v[42:45], v[10:13]
	v_mfma_f32_16x16x32_bf16 v[10:13], v[232:235], v[38:41], v[138:141]
	v_mfma_f32_16x16x32_bf16 v[74:77], v[236:239], v[42:45], v[10:13]
	v_mfma_f32_16x16x32_bf16 v[10:13], v[224:227], v[146:149], v[142:145]
	v_mfma_f32_16x16x32_bf16 v[38:41], v[228:231], v[180:183], v[10:13]
	v_mfma_f32_16x16x32_bf16 v[10:13], v[232:235], v[146:149], v[176:179]
	v_mfma_f32_16x16x32_bf16 v[42:45], v[236:239], v[180:183], v[10:13]
	v_mfma_f32_16x16x32_bf16 v[10:13], v[224:227], v[184:187], v[200:203]
	v_mfma_f32_16x16x32_bf16 v[22:25], v[228:231], v[188:191], v[10:13]
	v_mfma_f32_16x16x32_bf16 v[10:13], v[232:235], v[184:187], v[204:207]
	v_mfma_f32_16x16x32_bf16 v[26:29], v[236:239], v[188:191], v[10:13]
	v_mfma_f32_16x16x32_bf16 v[10:13], v[224:227], v[240:243], v[208:211]
	v_mfma_f32_16x16x32_bf16 v[14:17], v[228:231], v[248:251], v[10:13]
	v_mfma_f32_16x16x32_bf16 v[10:13], v[232:235], v[240:243], v[212:215]
	v_mfma_f32_16x16x32_bf16 v[10:13], v[236:239], v[248:251], v[10:13]
	s_setprio 0
	s_barrier
	s_and_saveexec_b64 s[14:15], s[6:7]
	s_cbranch_execz .LBB0_117
	s_barrier

; #define LDA(dst, b, h) for (int m = 0; m < 4; ++m) for (int k = 0; k < 2; ++k) \
;     dst[m][k] = *reinterpret_cast<const bf16x8*>((char*)SA(b, h) + lds_byte(wr * 64 + m * 16 + fr, k * 32 + fq * 8))
; #define LDB(dst, b, h) for (int n = 0; n < 2; ++n) for (int k = 0; k < 2; ++k) \
;     dst[n][k] = *reinterpret_cast<const bf16x8*>((char*)SB(b, h) + lds_byte(wc * 32 + n * 16 + fr, k * 32 + fq * 8))
; #define WAIT_V(n) asm volatile("s_waitcnt vmcnt(" #n ")" ::: "memory")
; #define BAR __builtin_amdgcn_s_barrier()
; #define SCHED __builtin_amdgcn_sched_barrier(0)
; #define TILE_COORDS(wg, pm_, pn_) do { constexpr int WGM = 8; const int nig = WGM * nN, gid = (wg) / nig, fm = gid * WGM, gsz = min(nM - fm, WGM); \
;     pm_ = fm + (((wg) % nig) % gsz); pn_ = ((wg) % nig) / gsz; } while (0)
; template <int EPI> ...
;     ...
;     int pm, pn; TILE_COORDS(wgid, pm, pn);
;     const int brow = pm * BM, bcol = pn * BM;
;     f32x4 acc[2][2][4][2] = {};
;     bf16x8 At[4][2], B0[2][2], B1[2][2];
;     if (wr == 1) BAR;
;     WAIT_V(0); BAR;
;     STAGE(SB(1, 0), Bt, bcol, 1); STAGE(SA(1, 0), A, brow, 1); STAGE(SB(1, 1), Bt, bcol + HALF, 1);
;     WAIT_V(6); BAR;
;     for (int t = 0; t < nt - 2; t += 2) {
;       LDB(B0, 0, 0); SCHED; LDA(At, 0, 0); STAGE(SA(1, 1), A, brow + HALF, t + 1);
.LBB0_540:
	s_or_b64 exec, exec, s[14:15]
	s_ashr_i32 s14, s24, 31
	s_lshr_b32 s14, s14, 25
	s_add_i32 s14, s24, s14
	s_ashr_i32 s15, s14, 7
	s_and_b32 s14, s14, 0xff80
	s_sub_i32 s14, s24, s14
	s_lshl_b32 s22, s15, 3
	s_bfe_i32 s15, s14, 0x80000
	s_bfe_u32 s15, s15, 0x3000c
	s_add_i32 s15, s14, s15
	s_bfe_i32 s16, s15, 0x80000
	s_sext_i32_i16 s16, s16
	s_and_b32 s15, s15, 0xf8
	s_ashr_i32 s23, s16, 3
	s_sub_i32 s14, s14, s15
	s_lshl_b32 s16, s23, 1
	s_sext_i32_i8 s14, s14
	s_ashr_i32 s17, s16, 31
	s_add_i32 s22, s22, s14
	s_lshl_b64 s[14:15], s[16:17], 20
	s_add_u32 s25, s18, s14
	s_addc_u32 s26, s19, s15
	s_add_u32 s14, s25, 0x4000
	v_add_u32_e32 v0, s46, v130
	s_addc_u32 s15, s26, 0
	v_readfirstlane_b32 s17, v0
	s_waitcnt vmcnt(0)
	s_barrier
	s_mov_b32 m0, s17
	s_waitcnt lgkmcnt(0)
	v_lshl_add_u64 v[2:3], s[14:15], 0, v[130:131]
	v_add_u32_e32 v134, 0x2000, v0
	global_load_lds_dwordx4 v[2:3], off
	v_lshl_add_u64 v[2:3], s[14:15], 0, v[132:133]
	v_readfirstlane_b32 s14, v134
	s_mov_b32 m0, s14
	s_lshl_b32 s14, s22, 1
	s_ashr_i32 s15, s14, 31
	s_lshl_b64 s[28:29], s[14:15], 20
	s_add_u32 s15, s10, s28
	s_addc_u32 s27, s11, s29
	s_add_u32 s28, s15, 0x4000
	v_add_u32_e32 v135, 0x8000, v161
	s_addc_u32 s29, s27, 0
	v_readfirstlane_b32 s17, v135
	v_add_u32_e32 v136, 0xa000, v161
	global_load_lds_dwordx4 v[2:3], off
	s_mov_b32 m0, s17
	v_lshl_add_u64 v[2:3], s[28:29], 0, v[130:131]
	v_readfirstlane_b32 s17, v136
	s_or_b32 s16, s16, 1
	global_load_lds_dwordx4 v[2:3], off
	s_mov_b32 m0, s17
	s_ashr_i32 s17, s16, 31
	s_lshl_b64 s[16:17], s[16:17], 20
	s_add_u32 s16, s18, s16
	s_addc_u32 s17, s19, s17
	s_add_u32 s16, s16, 0x4000
	v_add_u32_e32 v137, s91, v130
	v_lshl_add_u64 v[2:3], s[28:29], 0, v[132:133]
	s_addc_u32 s17, s17, 0
	v_readfirstlane_b32 s28, v137
	global_load_lds_dwordx4 v[2:3], off
	s_mov_b32 m0, s28
	v_lshl_add_u64 v[2:3], s[16:17], 0, v[130:131]
	v_add_u32_e32 v138, 0x2000, v137
	global_load_lds_dwordx4 v[2:3], off
	v_lshl_add_u64 v[2:3], s[16:17], 0, v[132:133]
	v_readfirstlane_b32 s16, v138
	s_mov_b32 m0, s16
	s_mov_b32 s28, -2
	global_load_lds_dwordx4 v[2:3], off
	s_waitcnt vmcnt(6)
	v_mov_b32_e32 v2, 0
	s_mov_b64 s[16:17], 0
	v_mov_b32_e32 v3, v2
	v_mov_b32_e32 v4, v2
	v_mov_b32_e32 v5, v2
	v_mov_b32_e32 v6, v2
	v_mov_b32_e32 v7, v2
	v_mov_b32_e32 v8, v2
	v_mov_b32_e32 v9, v2
	v_mov_b32_e32 v10, v2
	v_mov_b32_e32 v11, v2
	v_mov_b32_e32 v12, v2
	v_mov_b32_e32 v13, v2
	v_mov_b32_e32 v14, v2
	v_mov_b32_e32 v15, v2
	v_mov_b32_e32 v16, v2
	v_mov_b32_e32 v17, v2
	v_mov_b32_e32 v18, v2
	v_mov_b32_e32 v19, v2
	v_mov_b32_e32 v20, v2
	v_mov_b32_e32 v21, v2
	v_mov_b32_e32 v22, v2
	v_mov_b32_e32 v23, v2
	v_mov_b32_e32 v24, v2
	v_mov_b32_e32 v25, v2
	v_mov_b32_e32 v26, v2
	v_mov_b32_e32 v27, v2
	v_mov_b32_e32 v28, v2
	v_mov_b32_e32 v29, v2
	v_mov_b32_e32 v30, v2
	v_mov_b32_e32 v31, v2
	v_mov_b32_e32 v32, v2
	v_mov_b32_e32 v33, v2
	v_mov_b32_e32 v34, v2
	v_mov_b32_e32 v35, v2
	v_mov_b32_e32 v36, v2
	v_mov_b32_e32 v37, v2
	v_mov_b32_e32 v38, v2
	v_mov_b32_e32 v39, v2
	v_mov_b32_e32 v40, v2
	v_mov_b32_e32 v41, v2
	v_mov_b32_e32 v42, v2
	v_mov_b32_e32 v43, v2
	v_mov_b32_e32 v44, v2
	v_mov_b32_e32 v45, v2
	v_mov_b32_e32 v46, v2
	v_mov_b32_e32 v47, v2
	v_mov_b32_e32 v48, v2
	v_mov_b32_e32 v49, v2
	v_mov_b32_e32 v50, v2
	v_mov_b32_e32 v51, v2
	v_mov_b32_e32 v52, v2
	v_mov_b32_e32 v53, v2
	v_mov_b32_e32 v54, v2
	v_mov_b32_e32 v55, v2
	v_mov_b32_e32 v56, v2
	v_mov_b32_e32 v57, v2
	v_mov_b32_e32 v58, v2
	v_mov_b32_e32 v59, v2
	v_mov_b32_e32 v60, v2
	v_mov_b32_e32 v61, v2
	v_mov_b32_e32 v62, v2
	v_mov_b32_e32 v63, v2
	v_mov_b32_e32 v64, v2
	v_mov_b32_e32 v65, v2
	v_mov_b32_e32 v66, v2
	v_mov_b32_e32 v67, v2
	v_mov_b32_e32 v68, v2
	v_mov_b32_e32 v69, v2
	v_mov_b32_e32 v70, v2
	v_mov_b32_e32 v71, v2
	v_mov_b32_e32 v72, v2
	v_mov_b32_e32 v73, v2
	v_mov_b32_e32 v74, v2
	v_mov_b32_e32 v75, v2
	v_mov_b32_e32 v76, v2
	v_mov_b32_e32 v77, v2
	v_mov_b32_e32 v78, v2
	v_mov_b32_e32 v79, v2
	v_mov_b32_e32 v80, v2
	v_mov_b32_e32 v81, v2
	v_mov_b32_e32 v82, v2
	v_mov_b32_e32 v83, v2
	v_mov_b32_e32 v84, v2
	v_mov_b32_e32 v85, v2
	v_mov_b32_e32 v86, v2
	v_mov_b32_e32 v87, v2
	v_mov_b32_e32 v88, v2
	v_mov_b32_e32 v89, v2
	v_mov_b32_e32 v90, v2
	v_mov_b32_e32 v91, v2
	v_mov_b32_e32 v92, v2
	v_mov_b32_e32 v93, v2
	v_mov_b32_e32 v94, v2
	v_mov_b32_e32 v95, v2
	v_mov_b32_e32 v96, v2
	v_mov_b32_e32 v97, v2
	v_mov_b32_e32 v98, v2
	v_mov_b32_e32 v99, v2
	v_mov_b32_e32 v100, v2
	v_mov_b32_e32 v101, v2
	v_mov_b32_e32 v102, v2
	v_mov_b32_e32 v103, v2
	v_mov_b32_e32 v104, v2
	v_mov_b32_e32 v105, v2
	v_mov_b32_e32 v106, v2
	v_mov_b32_e32 v107, v2
	v_mov_b32_e32 v108, v2
	v_mov_b32_e32 v109, v2
	v_mov_b32_e32 v110, v2
	v_mov_b32_e32 v111, v2
	v_mov_b32_e32 v112, v2
	v_mov_b32_e32 v113, v2
	v_mov_b32_e32 v114, v2
	v_mov_b32_e32 v115, v2
	v_mov_b32_e32 v116, v2
	v_mov_b32_e32 v117, v2
	v_mov_b32_e32 v118, v2
	v_mov_b32_e32 v119, v2
	v_mov_b32_e32 v120, v2
	v_mov_b32_e32 v121, v2
	v_mov_b32_e32 v122, v2
	v_mov_b32_e32 v123, v2
	v_mov_b32_e32 v124, v2
	v_mov_b32_e32 v125, v2
	v_mov_b32_e32 v126, v2
	v_mov_b32_e32 v127, v2
	v_mov_b32_e32 v128, v2
	v_mov_b32_e32 v129, v2
	s_barrier
	v_readfirstlane_b32 s32, v161
	v_add_u32_e32 v141, 0xc000, v161
	v_add_u32_e32 v142, 0xe000, v161
	v_add_u32_e32 v139, 0x2000, v162
	v_add_u32_e32 v140, 0x2000, v164
	ds_read_b128 v[144:147], v167
	ds_read_b128 v[148:151], v167 offset:1024
	ds_read_b128 v[152:155], v167 offset:2048
	ds_read_b128 v[156:159], v167 offset:3072
; #define LDA(dst, b, h) for (int m = 0; m < 4; ++m) for (int k = 0; k < 2; ++k) \
;     dst[m][k] = *reinterpret_cast<const bf16x8*>((char*)SA(b, h) + lds_byte(wr * 64 + m * 16 + fr, k * 32 + fq * 8))
; #define LDB(dst, b, h) for (int n = 0; n < 2; ++n) for (int k = 0; k < 2; ++k) \
;     dst[n][k] = *reinterpret_cast<const bf16x8*>((char*)SB(b, h) + lds_byte(wc * 32 + n * 16 + fr, k * 32 + fq * 8))
; #define MMA(ai, bj, At, Bt_) do { __builtin_amdgcn_s_setprio(1); \
;     for (int m = 0; m < 4; ++m) for (int n = 0; n < 2; ++n) for (int k = 0; k < 2; ++k) \
;       acc[ai][bj][m][n] = __builtin_amdgcn_mfma_f32_16x16x32_bf16(Bt_[n][k], At[m][k], acc[ai][bj][m][n], 0, 0, 0); \
;     __builtin_amdgcn_s_setprio(0); } while (0)
; #define WAIT_V(n) asm volatile("s_waitcnt vmcnt(" #n ")" ::: "memory")
; #define WAIT_L(n) asm volatile("s_waitcnt lgkmcnt(" #n ")" ::: "memory")
; #define BAR __builtin_amdgcn_s_barrier()
; #define SCHED __builtin_amdgcn_sched_barrier(0)
; template <int EPI> ...
;     ...
;       LDB(B0, 0, 0); SCHED; LDA(At, 0, 0); STAGE(SA(1, 1), A, brow + HALF, t + 1);
;       WAIT_L(8); BAR; WAIT_L(0); MMA(0, 0, At, B0); BAR; SCHED;
;       LDB(B1, 0, 1); STAGE(SB(0, 0), Bt, bcol, t + 2);
;       BAR; WAIT_L(0); MMA(0, 1, At, B1); BAR;
;       LDA(At, 0, 1); STAGE(SA(0, 0), A, brow, t + 2);
;       BAR; WAIT_L(0); MMA(1, 0, At, B0); BAR; SCHED;
;       STAGE(SB(0, 1), Bt, bcol + HALF, t + 2);
;       WAIT_V(6); BAR; MMA(1, 1, At, B1); BAR;
;       LDB(B0, 1, 0); SCHED; LDA(At, 1, 0); STAGE(SA(0, 1), A, brow + HALF, t + 2);
.LBB0_541:
	s_add_u32 s29, s15, s16
	s_addc_u32 s30, s27, s17
	s_add_u32 s34, s29, 0x104000
	s_addc_u32 s35, s30, 0
	ds_read_b128 v[176:179], v168
	ds_read_b128 v[180:183], v168 offset:1024
	ds_read_b128 v[184:187], v169
	ds_read_b128 v[188:191], v169 offset:1024
	ds_read_b128 v[200:203], v170
	ds_read_b128 v[204:207], v170 offset:1024
	ds_read_b128 v[208:211], v171
	ds_read_b128 v[212:215], v171 offset:1024
	s_add_u32 m0, s32, 0xc000
	s_nop 0
	global_load_lds_dwordx4 v130, s[34:35]
	s_add_u32 m0, s32, 0xe000
	s_nop 0
	global_load_lds_dwordx4 v132, s[34:35]
	s_waitcnt lgkmcnt(8)
	s_barrier
	s_waitcnt lgkmcnt(0)
	s_setprio 1
	s_waitcnt lgkmcnt(0)
	v_mfma_f32_16x16x32_bf16 v[126:129], v[144:147], v[176:179], v[126:129]
	v_mfma_f32_16x16x32_bf16 v[122:125], v[152:155], v[176:179], v[122:125]
	v_mfma_f32_16x16x32_bf16 v[118:121], v[144:147], v[184:187], v[118:121]
	v_mfma_f32_16x16x32_bf16 v[114:117], v[152:155], v[184:187], v[114:117]
	v_mfma_f32_16x16x32_bf16 v[110:113], v[144:147], v[200:203], v[110:113]
	v_mfma_f32_16x16x32_bf16 v[106:109], v[152:155], v[200:203], v[106:109]
	v_mfma_f32_16x16x32_bf16 v[102:105], v[144:147], v[208:211], v[102:105]
	v_mfma_f32_16x16x32_bf16 v[98:101], v[152:155], v[208:211], v[98:101]
	v_mfma_f32_16x16x32_bf16 v[126:129], v[148:151], v[180:183], v[126:129]
	v_mfma_f32_16x16x32_bf16 v[122:125], v[156:159], v[180:183], v[122:125]
	v_mfma_f32_16x16x32_bf16 v[118:121], v[148:151], v[188:191], v[118:121]
	v_mfma_f32_16x16x32_bf16 v[114:117], v[156:159], v[188:191], v[114:117]
	v_mfma_f32_16x16x32_bf16 v[110:113], v[148:151], v[204:207], v[110:113]
	v_mfma_f32_16x16x32_bf16 v[106:109], v[156:159], v[204:207], v[106:109]
	v_mfma_f32_16x16x32_bf16 v[102:105], v[148:151], v[212:215], v[102:105]
	v_mfma_f32_16x16x32_bf16 v[98:101], v[156:159], v[212:215], v[98:101]
	s_setprio 0
	s_barrier
	s_add_u32 s31, s25, s16
	s_addc_u32 s34, s26, s17
	s_add_u32 s36, s31, 0x8000
	s_addc_u32 s37, s34, 0
	ds_read_b128 v[216:219], v172
	ds_read_b128 v[220:223], v172 offset:1024
	ds_read_b128 v[224:227], v172 offset:2048
	ds_read_b128 v[228:231], v172 offset:3072
	s_add_u32 m0, s32, 0x10000
	s_nop 0
	global_load_lds_dwordx4 v130, s[36:37]
	s_add_u32 m0, s32, 0x12000
	s_nop 0
	global_load_lds_dwordx4 v132, s[36:37]
	s_barrier
	s_waitcnt lgkmcnt(0)
	s_setprio 1
	s_waitcnt lgkmcnt(0)
	v_mfma_f32_16x16x32_bf16 v[94:97], v[216:219], v[176:179], v[94:97]
	v_mfma_f32_16x16x32_bf16 v[90:93], v[224:227], v[176:179], v[90:93]
	v_mfma_f32_16x16x32_bf16 v[86:89], v[216:219], v[184:187], v[86:89]
	v_mfma_f32_16x16x32_bf16 v[82:85], v[224:227], v[184:187], v[82:85]
	v_mfma_f32_16x16x32_bf16 v[78:81], v[216:219], v[200:203], v[78:81]
	v_mfma_f32_16x16x32_bf16 v[74:77], v[224:227], v[200:203], v[74:77]
	v_mfma_f32_16x16x32_bf16 v[70:73], v[216:219], v[208:211], v[70:73]
	v_mfma_f32_16x16x32_bf16 v[66:69], v[224:227], v[208:211], v[66:69]
	v_mfma_f32_16x16x32_bf16 v[94:97], v[220:223], v[180:183], v[94:97]
	v_mfma_f32_16x16x32_bf16 v[90:93], v[228:231], v[180:183], v[90:93]
	v_mfma_f32_16x16x32_bf16 v[86:89], v[220:223], v[188:191], v[86:89]
	v_mfma_f32_16x16x32_bf16 v[82:85], v[228:231], v[188:191], v[82:85]
	v_mfma_f32_16x16x32_bf16 v[78:81], v[220:223], v[204:207], v[78:81]
	v_mfma_f32_16x16x32_bf16 v[74:77], v[228:231], v[204:207], v[74:77]
	v_mfma_f32_16x16x32_bf16 v[70:73], v[220:223], v[212:215], v[70:73]
	v_mfma_f32_16x16x32_bf16 v[66:69], v[228:231], v[212:215], v[66:69]
	s_setprio 0
	s_add_u32 s36, s29, 0x8000
	s_addc_u32 s37, s30, 0
	s_barrier
	ds_read_b128 v[176:179], v168 offset:16384
	ds_read_b128 v[180:183], v168 offset:17408
	ds_read_b128 v[184:187], v169 offset:16384
	ds_read_b128 v[188:191], v169 offset:17408
	ds_read_b128 v[200:203], v170 offset:16384
	ds_read_b128 v[204:207], v170 offset:17408
	ds_read_b128 v[208:211], v171 offset:16384
	ds_read_b128 v[212:215], v171 offset:17408
	s_add_u32 m0, s32, 0x0
	s_nop 0
	global_load_lds_dwordx4 v130, s[36:37]
	s_add_u32 m0, s32, 0x2000
	s_nop 0
	global_load_lds_dwordx4 v132, s[36:37]
	s_waitcnt vmcnt(10)
	s_barrier
	s_waitcnt lgkmcnt(0)
	s_setprio 1
	s_waitcnt lgkmcnt(0)
	v_mfma_f32_16x16x32_bf16 v[62:65], v[144:147], v[176:179], v[62:65]
	v_mfma_f32_16x16x32_bf16 v[58:61], v[152:155], v[176:179], v[58:61]
	v_mfma_f32_16x16x32_bf16 v[54:57], v[144:147], v[184:187], v[54:57]
	v_mfma_f32_16x16x32_bf16 v[50:53], v[152:155], v[184:187], v[50:53]
	v_mfma_f32_16x16x32_bf16 v[46:49], v[144:147], v[200:203], v[46:49]
	v_mfma_f32_16x16x32_bf16 v[42:45], v[152:155], v[200:203], v[42:45]
	v_mfma_f32_16x16x32_bf16 v[38:41], v[144:147], v[208:211], v[38:41]
	v_mfma_f32_16x16x32_bf16 v[34:37], v[152:155], v[208:211], v[34:37]
	v_mfma_f32_16x16x32_bf16 v[62:65], v[148:151], v[180:183], v[62:65]
	v_mfma_f32_16x16x32_bf16 v[58:61], v[156:159], v[180:183], v[58:61]
	v_mfma_f32_16x16x32_bf16 v[54:57], v[148:151], v[188:191], v[54:57]
	v_mfma_f32_16x16x32_bf16 v[50:53], v[156:159], v[188:191], v[50:53]
	v_mfma_f32_16x16x32_bf16 v[46:49], v[148:151], v[204:207], v[46:49]
	v_mfma_f32_16x16x32_bf16 v[42:45], v[156:159], v[204:207], v[42:45]
	v_mfma_f32_16x16x32_bf16 v[38:41], v[148:151], v[212:215], v[38:41]
	v_mfma_f32_16x16x32_bf16 v[34:37], v[156:159], v[212:215], v[34:37]
	s_setprio 0
	s_barrier
	ds_read_b128 v[144:147], v173
	ds_read_b128 v[148:151], v173 offset:1024
	ds_read_b128 v[152:155], v173 offset:2048
	ds_read_b128 v[156:159], v173 offset:3072
	s_add_u32 s36, s31, 0x108000
	s_addc_u32 s37, s34, 0
	s_add_u32 m0, s32, 0x14000
	s_nop 0
	global_load_lds_dwordx4 v130, s[36:37]
	s_add_u32 m0, s32, 0x16000
	s_nop 0
	global_load_lds_dwordx4 v132, s[36:37]
	s_waitcnt vmcnt(6)
	s_barrier
; #define LDA(dst, b, h) for (int m = 0; m < 4; ++m) for (int k = 0; k < 2; ++k) \
;     dst[m][k] = *reinterpret_cast<const bf16x8*>((char*)SA(b, h) + lds_byte(wr * 64 + m * 16 + fr, k * 32 + fq * 8))
; #define LDB(dst, b, h) for (int n = 0; n < 2; ++n) for (int k = 0; k < 2; ++k) \
;     dst[n][k] = *reinterpret_cast<const bf16x8*>((char*)SB(b, h) + lds_byte(wc * 32 + n * 16 + fr, k * 32 + fq * 8))
; #define MMA(ai, bj, At, Bt_) do { __builtin_amdgcn_s_setprio(1); \
;     for (int m = 0; m < 4; ++m) for (int n = 0; n < 2; ++n) for (int k = 0; k < 2; ++k) \
;       acc[ai][bj][m][n] = __builtin_amdgcn_mfma_f32_16x16x32_bf16(Bt_[n][k], At[m][k], acc[ai][bj][m][n], 0, 0, 0); \
;     __builtin_amdgcn_s_setprio(0); } while (0)
; #define WAIT_V(n) asm volatile("s_waitcnt vmcnt(" #n ")" ::: "memory")
; #define WAIT_L(n) asm volatile("s_waitcnt lgkmcnt(" #n ")" ::: "memory")
; #define BAR __builtin_amdgcn_s_barrier()
; #define SCHED __builtin_amdgcn_sched_barrier(0)
; template <int EPI> ...
;     ...
;       WAIT_V(6); BAR; MMA(1, 1, At, B1); BAR;
;       LDB(B0, 1, 0); SCHED; LDA(At, 1, 0); STAGE(SA(0, 1), A, brow + HALF, t + 2);
;       WAIT_L(8); BAR; WAIT_L(0); MMA(0, 0, At, B0); BAR; SCHED;
;       LDB(B1, 1, 1); STAGE(SB(1, 0), Bt, bcol, t + 3);
;       BAR; WAIT_L(0); MMA(0, 1, At, B1); BAR;
;       LDA(At, 1, 1); STAGE(SA(1, 0), A, brow, t + 3);
;       BAR; WAIT_L(0); MMA(1, 0, At, B0); BAR; SCHED;
	s_setprio 1
	v_mfma_f32_16x16x32_bf16 v[30:33], v[216:219], v[176:179], v[30:33]
	v_mfma_f32_16x16x32_bf16 v[26:29], v[224:227], v[176:179], v[26:29]
	v_mfma_f32_16x16x32_bf16 v[22:25], v[216:219], v[184:187], v[22:25]
	v_mfma_f32_16x16x32_bf16 v[18:21], v[224:227], v[184:187], v[18:21]
	v_mfma_f32_16x16x32_bf16 v[14:17], v[216:219], v[200:203], v[14:17]
	v_mfma_f32_16x16x32_bf16 v[10:13], v[224:227], v[200:203], v[10:13]
	v_mfma_f32_16x16x32_bf16 v[6:9], v[216:219], v[208:211], v[6:9]
	v_mfma_f32_16x16x32_bf16 v[2:5], v[224:227], v[208:211], v[2:5]
	v_mfma_f32_16x16x32_bf16 v[30:33], v[220:223], v[180:183], v[30:33]
	v_mfma_f32_16x16x32_bf16 v[26:29], v[228:231], v[180:183], v[26:29]
	v_mfma_f32_16x16x32_bf16 v[22:25], v[220:223], v[188:191], v[22:25]
	v_mfma_f32_16x16x32_bf16 v[18:21], v[228:231], v[188:191], v[18:21]
	v_mfma_f32_16x16x32_bf16 v[14:17], v[220:223], v[204:207], v[14:17]
	v_mfma_f32_16x16x32_bf16 v[10:13], v[228:231], v[204:207], v[10:13]
	v_mfma_f32_16x16x32_bf16 v[6:9], v[220:223], v[212:215], v[6:9]
	v_mfma_f32_16x16x32_bf16 v[2:5], v[228:231], v[212:215], v[2:5]
	s_setprio 0
	s_barrier
	s_add_u32 s36, s29, 0x108000
	s_addc_u32 s37, s30, 0
	ds_read_b128 v[176:179], v168 offset:32768
	ds_read_b128 v[180:183], v168 offset:33792
	ds_read_b128 v[184:187], v169 offset:32768
	ds_read_b128 v[188:191], v169 offset:33792
	ds_read_b128 v[200:203], v170 offset:32768
	ds_read_b128 v[204:207], v170 offset:33792
	ds_read_b128 v[208:211], v171 offset:32768
	ds_read_b128 v[212:215], v171 offset:33792
	s_add_u32 m0, s32, 0x4000
	s_nop 0
	global_load_lds_dwordx4 v130, s[36:37]
	s_add_u32 m0, s32, 0x6000
	s_nop 0
	global_load_lds_dwordx4 v132, s[36:37]
	s_waitcnt lgkmcnt(8)
	s_barrier
	s_waitcnt lgkmcnt(0)
	s_setprio 1
	s_waitcnt lgkmcnt(0)
	v_mfma_f32_16x16x32_bf16 v[126:129], v[144:147], v[176:179], v[126:129]
	v_mfma_f32_16x16x32_bf16 v[122:125], v[152:155], v[176:179], v[122:125]
	v_mfma_f32_16x16x32_bf16 v[118:121], v[144:147], v[184:187], v[118:121]
	v_mfma_f32_16x16x32_bf16 v[114:117], v[152:155], v[184:187], v[114:117]
	v_mfma_f32_16x16x32_bf16 v[110:113], v[144:147], v[200:203], v[110:113]
	v_mfma_f32_16x16x32_bf16 v[106:109], v[152:155], v[200:203], v[106:109]
	v_mfma_f32_16x16x32_bf16 v[102:105], v[144:147], v[208:211], v[102:105]
	v_mfma_f32_16x16x32_bf16 v[98:101], v[152:155], v[208:211], v[98:101]
	v_mfma_f32_16x16x32_bf16 v[126:129], v[148:151], v[180:183], v[126:129]
	v_mfma_f32_16x16x32_bf16 v[122:125], v[156:159], v[180:183], v[122:125]
	v_mfma_f32_16x16x32_bf16 v[118:121], v[148:151], v[188:191], v[118:121]
	v_mfma_f32_16x16x32_bf16 v[114:117], v[156:159], v[188:191], v[114:117]
	v_mfma_f32_16x16x32_bf16 v[110:113], v[148:151], v[204:207], v[110:113]
	v_mfma_f32_16x16x32_bf16 v[106:109], v[156:159], v[204:207], v[106:109]
	v_mfma_f32_16x16x32_bf16 v[102:105], v[148:151], v[212:215], v[102:105]
	v_mfma_f32_16x16x32_bf16 v[98:101], v[156:159], v[212:215], v[98:101]
	s_setprio 0
	s_barrier
	s_add_u32 s36, s31, 0xc000
	s_addc_u32 s37, s34, 0
	ds_read_b128 v[216:219], v174
	ds_read_b128 v[220:223], v174 offset:1024
	ds_read_b128 v[224:227], v174 offset:2048
	ds_read_b128 v[228:231], v174 offset:3072
	s_add_u32 m0, s32, 0x18000
	s_nop 0
	global_load_lds_dwordx4 v130, s[36:37]
	s_add_u32 m0, s32, 0x1a000
	s_nop 0
	global_load_lds_dwordx4 v132, s[36:37]
	s_barrier
	s_waitcnt lgkmcnt(0)
	s_setprio 1
	s_waitcnt lgkmcnt(0)
	v_mfma_f32_16x16x32_bf16 v[94:97], v[216:219], v[176:179], v[94:97]
	v_mfma_f32_16x16x32_bf16 v[90:93], v[224:227], v[176:179], v[90:93]
	v_mfma_f32_16x16x32_bf16 v[86:89], v[216:219], v[184:187], v[86:89]
	v_mfma_f32_16x16x32_bf16 v[82:85], v[224:227], v[184:187], v[82:85]
	v_mfma_f32_16x16x32_bf16 v[78:81], v[216:219], v[200:203], v[78:81]
	v_mfma_f32_16x16x32_bf16 v[74:77], v[224:227], v[200:203], v[74:77]
	v_mfma_f32_16x16x32_bf16 v[70:73], v[216:219], v[208:211], v[70:73]
	v_mfma_f32_16x16x32_bf16 v[66:69], v[224:227], v[208:211], v[66:69]
	v_mfma_f32_16x16x32_bf16 v[94:97], v[220:223], v[180:183], v[94:97]
	v_mfma_f32_16x16x32_bf16 v[90:93], v[228:231], v[180:183], v[90:93]
	v_mfma_f32_16x16x32_bf16 v[86:89], v[220:223], v[188:191], v[86:89]
	v_mfma_f32_16x16x32_bf16 v[82:85], v[228:231], v[188:191], v[82:85]
	v_mfma_f32_16x16x32_bf16 v[78:81], v[220:223], v[204:207], v[78:81]
	v_mfma_f32_16x16x32_bf16 v[74:77], v[228:231], v[204:207], v[74:77]
	v_mfma_f32_16x16x32_bf16 v[70:73], v[220:223], v[212:215], v[70:73]
	v_mfma_f32_16x16x32_bf16 v[66:69], v[228:231], v[212:215], v[66:69]
	s_setprio 0
	s_add_u32 s36, s29, 0xc000
	s_addc_u32 s37, s30, 0
	s_barrier
	ds_read_b128 v[176:179], v168 offset:49152
	ds_read_b128 v[180:183], v168 offset:50176
	ds_read_b128 v[184:187], v169 offset:49152
	ds_read_b128 v[188:191], v169 offset:50176
	ds_read_b128 v[200:203], v170 offset:49152
	ds_read_b128 v[204:207], v170 offset:50176
	ds_read_b128 v[208:211], v171 offset:49152
	ds_read_b128 v[212:215], v171 offset:50176
	s_add_u32 m0, s32, 0x8000
	s_nop 0
	global_load_lds_dwordx4 v130, s[36:37]
	s_add_u32 m0, s32, 0xa000
	s_nop 0
	global_load_lds_dwordx4 v132, s[36:37]
	s_waitcnt vmcnt(10)
	s_barrier
; #define LDA(dst, b, h) for (int m = 0; m < 4; ++m) for (int k = 0; k < 2; ++k) \
;     dst[m][k] = *reinterpret_cast<const bf16x8*>((char*)SA(b, h) + lds_byte(wr * 64 + m * 16 + fr, k * 32 + fq * 8))
; #define LDB(dst, b, h) for (int n = 0; n < 2; ++n) for (int k = 0; k < 2; ++k) \
;     dst[n][k] = *reinterpret_cast<const bf16x8*>((char*)SB(b, h) + lds_byte(wc * 32 + n * 16 + fr, k * 32 + fq * 8))
; #define MMA(ai, bj, At, Bt_) do { __builtin_amdgcn_s_setprio(1); \
;     for (int m = 0; m < 4; ++m) for (int n = 0; n < 2; ++n) for (int k = 0; k < 2; ++k) \
;       acc[ai][bj][m][n] = __builtin_amdgcn_mfma_f32_16x16x32_bf16(Bt_[n][k], At[m][k], acc[ai][bj][m][n], 0, 0, 0); \
;     __builtin_amdgcn_s_setprio(0); } while (0)
; #define WAIT_V(n) asm volatile("s_waitcnt vmcnt(" #n ")" ::: "memory")
; #define WAIT_L(n) asm volatile("s_waitcnt lgkmcnt(" #n ")" ::: "memory")
; #define BAR __builtin_amdgcn_s_barrier()
; #define SCHED __builtin_amdgcn_sched_barrier(0)
; template <int EPI> ...
;     ...
;       BAR; WAIT_L(0); MMA(1, 0, At, B0); BAR; SCHED;
;       STAGE(SB(1, 1), Bt, bcol + HALF, t + 3);
;       WAIT_V(6); BAR; MMA(1, 1, At, B1); BAR;
;     }
;     { LDB(B0, 0, 0); LDA(At, 0, 0); STAGE(SA(1, 1), A, brow + HALF, nt - 1);
;       BAR; WAIT_L(0); MMA(0, 0, At, B0); BAR;
;       LDB(B1, 0, 1); BAR; WAIT_L(0); MMA(0, 1, At, B1); BAR;
	s_waitcnt lgkmcnt(0)
	s_setprio 1
	s_waitcnt lgkmcnt(0)
	v_mfma_f32_16x16x32_bf16 v[62:65], v[144:147], v[176:179], v[62:65]
	v_mfma_f32_16x16x32_bf16 v[58:61], v[152:155], v[176:179], v[58:61]
	v_mfma_f32_16x16x32_bf16 v[54:57], v[144:147], v[184:187], v[54:57]
	v_mfma_f32_16x16x32_bf16 v[50:53], v[152:155], v[184:187], v[50:53]
	v_mfma_f32_16x16x32_bf16 v[46:49], v[144:147], v[200:203], v[46:49]
	v_mfma_f32_16x16x32_bf16 v[42:45], v[152:155], v[200:203], v[42:45]
	v_mfma_f32_16x16x32_bf16 v[38:41], v[144:147], v[208:211], v[38:41]
	v_mfma_f32_16x16x32_bf16 v[34:37], v[152:155], v[208:211], v[34:37]
	v_mfma_f32_16x16x32_bf16 v[62:65], v[148:151], v[180:183], v[62:65]
	v_mfma_f32_16x16x32_bf16 v[58:61], v[156:159], v[180:183], v[58:61]
	v_mfma_f32_16x16x32_bf16 v[54:57], v[148:151], v[188:191], v[54:57]
	v_mfma_f32_16x16x32_bf16 v[50:53], v[156:159], v[188:191], v[50:53]
	v_mfma_f32_16x16x32_bf16 v[46:49], v[148:151], v[204:207], v[46:49]
	v_mfma_f32_16x16x32_bf16 v[42:45], v[156:159], v[204:207], v[42:45]
	v_mfma_f32_16x16x32_bf16 v[38:41], v[148:151], v[212:215], v[38:41]
	v_mfma_f32_16x16x32_bf16 v[34:37], v[156:159], v[212:215], v[34:37]
	s_setprio 0
	s_barrier
	ds_read_b128 v[144:147], v167
	ds_read_b128 v[148:151], v167 offset:1024
	ds_read_b128 v[152:155], v167 offset:2048
	ds_read_b128 v[156:159], v167 offset:3072
	s_add_u32 s30, s31, 0x10c000
	s_addc_u32 s31, s34, 0
	s_add_u32 m0, s32, 0x1c000
	s_nop 0
	global_load_lds_dwordx4 v130, s[30:31]
	s_add_u32 m0, s32, 0x1e000
	s_nop 0
	global_load_lds_dwordx4 v132, s[30:31]
	s_waitcnt vmcnt(6)
	s_barrier
	s_setprio 1
	v_mfma_f32_16x16x32_bf16 v[30:33], v[216:219], v[176:179], v[30:33]
	v_mfma_f32_16x16x32_bf16 v[26:29], v[224:227], v[176:179], v[26:29]
	v_mfma_f32_16x16x32_bf16 v[22:25], v[216:219], v[184:187], v[22:25]
	v_mfma_f32_16x16x32_bf16 v[18:21], v[224:227], v[184:187], v[18:21]
	v_mfma_f32_16x16x32_bf16 v[14:17], v[216:219], v[200:203], v[14:17]
	v_mfma_f32_16x16x32_bf16 v[10:13], v[224:227], v[200:203], v[10:13]
	v_mfma_f32_16x16x32_bf16 v[6:9], v[216:219], v[208:211], v[6:9]
	v_mfma_f32_16x16x32_bf16 v[2:5], v[224:227], v[208:211], v[2:5]
	v_mfma_f32_16x16x32_bf16 v[30:33], v[220:223], v[180:183], v[30:33]
	v_mfma_f32_16x16x32_bf16 v[26:29], v[228:231], v[180:183], v[26:29]
	v_mfma_f32_16x16x32_bf16 v[22:25], v[220:223], v[188:191], v[22:25]
	v_mfma_f32_16x16x32_bf16 v[18:21], v[228:231], v[188:191], v[18:21]
	v_mfma_f32_16x16x32_bf16 v[14:17], v[220:223], v[204:207], v[14:17]
	v_mfma_f32_16x16x32_bf16 v[10:13], v[228:231], v[204:207], v[10:13]
	v_mfma_f32_16x16x32_bf16 v[6:9], v[220:223], v[212:215], v[6:9]
	v_mfma_f32_16x16x32_bf16 v[2:5], v[228:231], v[212:215], v[2:5]
	s_setprio 0
	s_add_i32 s28, s28, 2
	s_add_u32 s16, s16, 0x8000
	s_addc_u32 s17, s17, 0
	s_cmp_lt_u32 s28, 60
	s_barrier
	s_cbranch_scc1 .LBB0_541
	s_or_b32 s14, s14, 1
	s_ashr_i32 s15, s14, 31
	s_lshl_b64 s[14:15], s[14:15], 20
	s_add_u32 s14, s10, s14
	s_addc_u32 s15, s11, s15
	s_add_u32 s14, s14, 0xfc000
	s_addc_u32 s15, s15, 0
	v_readfirstlane_b32 s16, v141
	ds_read_b128 v[134:137], v167
	ds_read_b128 v[144:147], v167 offset:1024
	ds_read_b128 v[148:151], v167 offset:2048
	ds_read_b128 v[152:155], v167 offset:3072
	ds_read_b128 v[156:159], v168
	ds_read_b128 v[176:179], v168 offset:1024
	ds_read_b128 v[180:183], v169
	ds_read_b128 v[184:187], v169 offset:1024
	ds_read_b128 v[188:191], v170
	ds_read_b128 v[200:203], v170 offset:1024
	ds_read_b128 v[204:207], v171
	ds_read_b128 v[208:211], v171 offset:1024
	s_mov_b32 m0, s16
	v_lshl_add_u64 v[212:213], s[14:15], 0, v[130:131]
	global_load_lds_dwordx4 v[212:213], off
	v_lshl_add_u64 v[212:213], s[14:15], 0, v[132:133]
	v_readfirstlane_b32 s14, v142
	s_mov_b32 m0, s14
	s_nop 0
	global_load_lds_dwordx4 v[212:213], off
	s_barrier
	s_waitcnt lgkmcnt(0)
	s_setprio 1
	s_waitcnt lgkmcnt(0)
	v_mfma_f32_16x16x32_bf16 v[126:129], v[134:137], v[156:159], v[126:129]
	v_mfma_f32_16x16x32_bf16 v[122:125], v[148:151], v[156:159], v[122:125]
	v_mfma_f32_16x16x32_bf16 v[118:121], v[134:137], v[180:183], v[118:121]
	v_mfma_f32_16x16x32_bf16 v[114:117], v[148:151], v[180:183], v[114:117]
	v_mfma_f32_16x16x32_bf16 v[102:105], v[134:137], v[204:207], v[102:105]
	v_mfma_f32_16x16x32_bf16 v[98:101], v[148:151], v[204:207], v[98:101]
	v_mfma_f32_16x16x32_bf16 v[126:129], v[144:147], v[176:179], v[126:129]
	v_mfma_f32_16x16x32_bf16 v[122:125], v[152:155], v[176:179], v[122:125]
	v_mfma_f32_16x16x32_bf16 v[118:121], v[144:147], v[184:187], v[118:121]
	v_mfma_f32_16x16x32_bf16 v[114:117], v[152:155], v[184:187], v[114:117]
	v_mfma_f32_16x16x32_bf16 v[110:113], v[134:137], v[188:191], v[110:113]
	v_mfma_f32_16x16x32_bf16 v[106:109], v[148:151], v[188:191], v[106:109]
	v_mfma_f32_16x16x32_bf16 v[102:105], v[144:147], v[208:211], v[102:105]
	v_mfma_f32_16x16x32_bf16 v[98:101], v[152:155], v[208:211], v[98:101]
	v_mfma_f32_16x16x32_bf16 v[212:215], v[144:147], v[200:203], v[110:113]
	v_mfma_f32_16x16x32_bf16 v[216:219], v[152:155], v[200:203], v[106:109]
	s_setprio 0
	s_barrier
	s_nop 1
	ds_read_b128 v[106:109], v172
	ds_read_b128 v[110:113], v172 offset:1024
	ds_read_b128 v[220:223], v172 offset:2048
	ds_read_b128 v[224:227], v172 offset:3072
	s_barrier
; #define LDA(dst, b, h) for (int m = 0; m < 4; ++m) for (int k = 0; k < 2; ++k) \
;     dst[m][k] = *reinterpret_cast<const bf16x8*>((char*)SA(b, h) + lds_byte(wr * 64 + m * 16 + fr, k * 32 + fq * 8))
; #define LDB(dst, b, h) for (int n = 0; n < 2; ++n) for (int k = 0; k < 2; ++k) \
;     dst[n][k] = *reinterpret_cast<const bf16x8*>((char*)SB(b, h) + lds_byte(wc * 32 + n * 16 + fr, k * 32 + fq * 8))
; #define MMA(ai, bj, At, Bt_) do { __builtin_amdgcn_s_setprio(1); \
;     for (int m = 0; m < 4; ++m) for (int n = 0; n < 2; ++n) for (int k = 0; k < 2; ++k) \
;       acc[ai][bj][m][n] = __builtin_amdgcn_mfma_f32_16x16x32_bf16(Bt_[n][k], At[m][k], acc[ai][bj][m][n], 0, 0, 0); \
;     __builtin_amdgcn_s_setprio(0); } while (0)
; #define WAIT_V(n) asm volatile("s_waitcnt vmcnt(" #n ")" ::: "memory")
; #define WAIT_L(n) asm volatile("s_waitcnt lgkmcnt(" #n ")" ::: "memory")
; #define BAR __builtin_amdgcn_s_barrier()
; template <int EPI> ...
;     ...
;       LDB(B1, 0, 1); BAR; WAIT_L(0); MMA(0, 1, At, B1); BAR;
;       LDA(At, 0, 1); WAIT_V(4); BAR; WAIT_L(0); MMA(1, 0, At, B0); MMA(1, 1, At, B1); BAR; }
;     { LDB(B0, 1, 0); LDA(At, 1, 0); WAIT_V(2); BAR; WAIT_L(0); MMA(0, 0, At, B0); BAR;
	s_waitcnt lgkmcnt(0)
	s_setprio 1
	s_waitcnt lgkmcnt(0)
	v_mfma_f32_16x16x32_bf16 v[86:89], v[106:109], v[180:183], v[86:89]
	v_mfma_f32_16x16x32_bf16 v[82:85], v[220:223], v[180:183], v[82:85]
	v_mfma_f32_16x16x32_bf16 v[70:73], v[106:109], v[204:207], v[70:73]
	v_mfma_f32_16x16x32_bf16 v[66:69], v[220:223], v[204:207], v[66:69]
	v_mfma_f32_16x16x32_bf16 v[94:97], v[106:109], v[156:159], v[94:97]
	v_mfma_f32_16x16x32_bf16 v[90:93], v[220:223], v[156:159], v[90:93]
	v_mfma_f32_16x16x32_bf16 v[86:89], v[110:113], v[184:187], v[86:89]
	v_mfma_f32_16x16x32_bf16 v[82:85], v[224:227], v[184:187], v[82:85]
	v_mfma_f32_16x16x32_bf16 v[78:81], v[106:109], v[188:191], v[78:81]
	v_mfma_f32_16x16x32_bf16 v[74:77], v[220:223], v[188:191], v[74:77]
	v_mfma_f32_16x16x32_bf16 v[70:73], v[110:113], v[208:211], v[70:73]
	v_mfma_f32_16x16x32_bf16 v[66:69], v[224:227], v[208:211], v[66:69]
	v_mfma_f32_16x16x32_bf16 v[228:231], v[110:113], v[176:179], v[94:97]
	v_mfma_f32_16x16x32_bf16 v[156:159], v[224:227], v[176:179], v[90:93]
	v_mfma_f32_16x16x32_bf16 v[176:179], v[110:113], v[200:203], v[78:81]
	v_mfma_f32_16x16x32_bf16 v[180:183], v[224:227], v[200:203], v[74:77]
	s_setprio 0
	s_barrier
	s_nop 0
	ds_read_b128 v[74:77], v168 offset:16384
	ds_read_b128 v[78:81], v168 offset:17408
	ds_read_b128 v[90:93], v169 offset:16384
	ds_read_b128 v[94:97], v169 offset:17408
	ds_read_b128 v[184:187], v170 offset:16384
	ds_read_b128 v[188:191], v170 offset:17408
	ds_read_b128 v[200:203], v171 offset:16384
	ds_read_b128 v[204:207], v171 offset:17408
	s_waitcnt vmcnt(4)
	s_barrier
	s_waitcnt lgkmcnt(0)
	s_setprio 1
	s_waitcnt lgkmcnt(0)
	v_mfma_f32_16x16x32_bf16 v[62:65], v[134:137], v[74:77], v[62:65]
	v_mfma_f32_16x16x32_bf16 v[58:61], v[148:151], v[74:77], v[58:61]
	v_mfma_f32_16x16x32_bf16 v[54:57], v[134:137], v[90:93], v[54:57]
	v_mfma_f32_16x16x32_bf16 v[50:53], v[148:151], v[90:93], v[50:53]
	v_mfma_f32_16x16x32_bf16 v[38:41], v[134:137], v[200:203], v[38:41]
	v_mfma_f32_16x16x32_bf16 v[34:37], v[148:151], v[200:203], v[34:37]
	v_mfma_f32_16x16x32_bf16 v[62:65], v[144:147], v[78:81], v[62:65]
	v_mfma_f32_16x16x32_bf16 v[58:61], v[152:155], v[78:81], v[58:61]
	v_mfma_f32_16x16x32_bf16 v[54:57], v[144:147], v[94:97], v[54:57]
	v_mfma_f32_16x16x32_bf16 v[50:53], v[152:155], v[94:97], v[50:53]
	v_mfma_f32_16x16x32_bf16 v[46:49], v[134:137], v[184:187], v[46:49]
	v_mfma_f32_16x16x32_bf16 v[42:45], v[148:151], v[184:187], v[42:45]
	v_mfma_f32_16x16x32_bf16 v[38:41], v[144:147], v[204:207], v[38:41]
	v_mfma_f32_16x16x32_bf16 v[34:37], v[152:155], v[204:207], v[34:37]
	v_mfma_f32_16x16x32_bf16 v[208:211], v[144:147], v[188:191], v[46:49]
	v_mfma_f32_16x16x32_bf16 v[232:235], v[152:155], v[188:191], v[42:45]
	s_setprio 0
	s_setprio 1
	v_mfma_f32_16x16x32_bf16 v[22:25], v[106:109], v[90:93], v[22:25]
	v_mfma_f32_16x16x32_bf16 v[18:21], v[220:223], v[90:93], v[18:21]
	v_mfma_f32_16x16x32_bf16 v[6:9], v[106:109], v[200:203], v[6:9]
	v_mfma_f32_16x16x32_bf16 v[2:5], v[220:223], v[200:203], v[2:5]
	v_mfma_f32_16x16x32_bf16 v[30:33], v[106:109], v[74:77], v[30:33]
	v_mfma_f32_16x16x32_bf16 v[26:29], v[220:223], v[74:77], v[26:29]
	v_mfma_f32_16x16x32_bf16 v[22:25], v[110:113], v[94:97], v[22:25]
	v_mfma_f32_16x16x32_bf16 v[18:21], v[224:227], v[94:97], v[18:21]
	v_mfma_f32_16x16x32_bf16 v[14:17], v[106:109], v[184:187], v[14:17]
	v_mfma_f32_16x16x32_bf16 v[10:13], v[220:223], v[184:187], v[10:13]
	v_mfma_f32_16x16x32_bf16 v[6:9], v[110:113], v[204:207], v[6:9]
	v_mfma_f32_16x16x32_bf16 v[2:5], v[224:227], v[204:207], v[2:5]
	v_mfma_f32_16x16x32_bf16 v[134:137], v[110:113], v[78:81], v[30:33]
	v_mfma_f32_16x16x32_bf16 v[142:145], v[224:227], v[78:81], v[26:29]
	v_mfma_f32_16x16x32_bf16 v[146:149], v[110:113], v[188:191], v[14:17]
	v_mfma_f32_16x16x32_bf16 v[150:153], v[224:227], v[188:191], v[10:13]
	s_setprio 0
	s_barrier
	s_nop 0
	ds_read_b128 v[10:13], v173
	ds_read_b128 v[14:17], v173 offset:1024
	ds_read_b128 v[184:187], v173 offset:2048
	ds_read_b128 v[188:191], v173 offset:3072
	ds_read_b128 v[26:29], v168 offset:32768
	ds_read_b128 v[30:33], v168 offset:33792
	ds_read_b128 v[42:45], v169 offset:32768
	ds_read_b128 v[46:49], v169 offset:33792
	ds_read_b128 v[200:203], v170 offset:32768
	ds_read_b128 v[204:207], v170 offset:33792
	ds_read_b128 v[220:223], v171 offset:32768
	ds_read_b128 v[224:227], v171 offset:33792
	s_waitcnt vmcnt(2)
	s_barrier
; #define LDA(dst, b, h) for (int m = 0; m < 4; ++m) for (int k = 0; k < 2; ++k) \
;     dst[m][k] = *reinterpret_cast<const bf16x8*>((char*)SA(b, h) + lds_byte(wr * 64 + m * 16 + fr, k * 32 + fq * 8))
; #define LDB(dst, b, h) for (int n = 0; n < 2; ++n) for (int k = 0; k < 2; ++k) \
;     dst[n][k] = *reinterpret_cast<const bf16x8*>((char*)SB(b, h) + lds_byte(wc * 32 + n * 16 + fr, k * 32 + fq * 8))
; #define MMA(ai, bj, At, Bt_) do { __builtin_amdgcn_s_setprio(1); \
;     for (int m = 0; m < 4; ++m) for (int n = 0; n < 2; ++n) for (int k = 0; k < 2; ++k) \
;       acc[ai][bj][m][n] = __builtin_amdgcn_mfma_f32_16x16x32_bf16(Bt_[n][k], At[m][k], acc[ai][bj][m][n], 0, 0, 0); \
;     __builtin_amdgcn_s_setprio(0); } while (0)
; #define WAIT_V(n) asm volatile("s_waitcnt vmcnt(" #n ")" ::: "memory")
; #define WAIT_L(n) asm volatile("s_waitcnt lgkmcnt(" #n ")" ::: "memory")
; #define BAR __builtin_amdgcn_s_barrier()
; template <int EPI> ...
;     ...
;       LDA(At, 0, 1); WAIT_V(4); BAR; WAIT_L(0); MMA(1, 0, At, B0); MMA(1, 1, At, B1); BAR; }
;     { LDB(B0, 1, 0); LDA(At, 1, 0); WAIT_V(2); BAR; WAIT_L(0); MMA(0, 0, At, B0); BAR;
;       LDB(B1, 1, 1); WAIT_V(0); BAR; WAIT_L(0); MMA(0, 1, At, B1); BAR;
;       LDA(At, 1, 1); BAR; WAIT_L(0); MMA(1, 0, At, B0); MMA(1, 1, At, B1); BAR; }
;     if (wr == 0) BAR;
	s_waitcnt lgkmcnt(0)
	s_setprio 1
	s_waitcnt lgkmcnt(0)
	v_mfma_f32_16x16x32_bf16 v[74:77], v[10:13], v[26:29], v[126:129]
	v_mfma_f32_16x16x32_bf16 v[126:129], v[14:17], v[30:33], v[74:77]
	v_mfma_f32_16x16x32_bf16 v[74:77], v[184:187], v[26:29], v[122:125]
	v_mfma_f32_16x16x32_bf16 v[122:125], v[188:191], v[30:33], v[74:77]
	v_mfma_f32_16x16x32_bf16 v[74:77], v[10:13], v[42:45], v[118:121]
	v_mfma_f32_16x16x32_bf16 v[110:113], v[14:17], v[46:49], v[74:77]
	v_mfma_f32_16x16x32_bf16 v[74:77], v[184:187], v[42:45], v[114:117]
	v_mfma_f32_16x16x32_bf16 v[106:109], v[188:191], v[46:49], v[74:77]
	v_mfma_f32_16x16x32_bf16 v[74:77], v[10:13], v[200:203], v[212:215]
	v_mfma_f32_16x16x32_bf16 v[94:97], v[14:17], v[204:207], v[74:77]
	v_mfma_f32_16x16x32_bf16 v[74:77], v[184:187], v[200:203], v[216:219]
	v_mfma_f32_16x16x32_bf16 v[90:93], v[188:191], v[204:207], v[74:77]
	v_mfma_f32_16x16x32_bf16 v[74:77], v[10:13], v[220:223], v[102:105]
	v_mfma_f32_16x16x32_bf16 v[78:81], v[14:17], v[224:227], v[74:77]
	v_mfma_f32_16x16x32_bf16 v[74:77], v[184:187], v[220:223], v[98:101]
	v_mfma_f32_16x16x32_bf16 v[74:77], v[188:191], v[224:227], v[74:77]
	s_setprio 0
	s_barrier
	ds_read_b128 v[212:215], v174
	ds_read_b128 v[216:219], v174 offset:1024
	ds_read_b128 v[236:239], v174 offset:2048
	ds_read_b128 v[240:243], v174 offset:3072
	s_waitcnt vmcnt(0)
	s_barrier
	s_waitcnt lgkmcnt(0)
	s_setprio 1
	s_waitcnt lgkmcnt(0)
	v_mfma_f32_16x16x32_bf16 v[98:101], v[212:215], v[26:29], v[228:231]
	v_mfma_f32_16x16x32_bf16 v[26:29], v[236:239], v[26:29], v[156:159]
	v_mfma_f32_16x16x32_bf16 v[114:117], v[240:243], v[30:33], v[26:29]
	v_mfma_f32_16x16x32_bf16 v[26:29], v[212:215], v[42:45], v[86:89]
	v_mfma_f32_16x16x32_bf16 v[102:105], v[216:219], v[46:49], v[26:29]
	v_mfma_f32_16x16x32_bf16 v[26:29], v[236:239], v[42:45], v[82:85]
	v_mfma_f32_16x16x32_bf16 v[118:121], v[216:219], v[30:33], v[98:101]
	v_mfma_f32_16x16x32_bf16 v[98:101], v[240:243], v[46:49], v[26:29]
	v_mfma_f32_16x16x32_bf16 v[26:29], v[212:215], v[200:203], v[176:179]
	v_mfma_f32_16x16x32_bf16 v[86:89], v[216:219], v[204:207], v[26:29]
	v_mfma_f32_16x16x32_bf16 v[26:29], v[236:239], v[200:203], v[180:183]
	v_mfma_f32_16x16x32_bf16 v[82:85], v[240:243], v[204:207], v[26:29]
	v_mfma_f32_16x16x32_bf16 v[26:29], v[212:215], v[220:223], v[70:73]
	v_mfma_f32_16x16x32_bf16 v[70:73], v[216:219], v[224:227], v[26:29]
	v_mfma_f32_16x16x32_bf16 v[26:29], v[236:239], v[220:223], v[66:69]
	v_mfma_f32_16x16x32_bf16 v[66:69], v[240:243], v[224:227], v[26:29]
	s_setprio 0
	s_barrier
	ds_read_b128 v[154:157], v168 offset:49152
	ds_read_b128 v[176:179], v168 offset:50176
	ds_read_b128 v[180:183], v169 offset:49152
	ds_read_b128 v[200:203], v169 offset:50176
	ds_read_b128 v[204:207], v170 offset:49152
	ds_read_b128 v[220:223], v170 offset:50176
	ds_read_b128 v[224:227], v171 offset:49152
	ds_read_b128 v[228:231], v171 offset:50176
	s_barrier
	s_waitcnt lgkmcnt(0)
	s_setprio 1
	s_waitcnt lgkmcnt(0)
	v_mfma_f32_16x16x32_bf16 v[26:29], v[10:13], v[154:157], v[62:65]
	v_mfma_f32_16x16x32_bf16 v[62:65], v[14:17], v[176:179], v[26:29]
	v_mfma_f32_16x16x32_bf16 v[26:29], v[184:187], v[154:157], v[58:61]
	v_mfma_f32_16x16x32_bf16 v[58:61], v[188:191], v[176:179], v[26:29]
	v_mfma_f32_16x16x32_bf16 v[26:29], v[10:13], v[180:183], v[54:57]
	v_mfma_f32_16x16x32_bf16 v[46:49], v[14:17], v[200:203], v[26:29]
	v_mfma_f32_16x16x32_bf16 v[26:29], v[184:187], v[180:183], v[50:53]
	v_mfma_f32_16x16x32_bf16 v[42:45], v[188:191], v[200:203], v[26:29]
	v_mfma_f32_16x16x32_bf16 v[26:29], v[10:13], v[204:207], v[208:211]
	v_mfma_f32_16x16x32_bf16 v[10:13], v[10:13], v[224:227], v[38:41]
	v_mfma_f32_16x16x32_bf16 v[30:33], v[14:17], v[220:223], v[26:29]
	v_mfma_f32_16x16x32_bf16 v[26:29], v[184:187], v[204:207], v[232:235]
	v_mfma_f32_16x16x32_bf16 v[14:17], v[14:17], v[228:231], v[10:13]
	v_mfma_f32_16x16x32_bf16 v[10:13], v[184:187], v[224:227], v[34:37]
	v_mfma_f32_16x16x32_bf16 v[26:29], v[188:191], v[220:223], v[26:29]
	v_mfma_f32_16x16x32_bf16 v[10:13], v[188:191], v[228:231], v[10:13]
	s_setprio 0
	s_setprio 1
	v_mfma_f32_16x16x32_bf16 v[34:37], v[212:215], v[154:157], v[134:137]
	v_mfma_f32_16x16x32_bf16 v[54:57], v[216:219], v[176:179], v[34:37]
	v_mfma_f32_16x16x32_bf16 v[34:37], v[236:239], v[154:157], v[142:145]
	v_mfma_f32_16x16x32_bf16 v[18:21], v[236:239], v[180:183], v[18:21]
	v_mfma_f32_16x16x32_bf16 v[50:53], v[240:243], v[176:179], v[34:37]
	v_mfma_f32_16x16x32_bf16 v[22:25], v[212:215], v[180:183], v[22:25]
	v_mfma_f32_16x16x32_bf16 v[34:37], v[240:243], v[200:203], v[18:21]
	v_mfma_f32_16x16x32_bf16 v[18:21], v[212:215], v[204:207], v[146:149]
	v_mfma_f32_16x16x32_bf16 v[38:41], v[216:219], v[200:203], v[22:25]
	v_mfma_f32_16x16x32_bf16 v[22:25], v[216:219], v[220:223], v[18:21]
	v_mfma_f32_16x16x32_bf16 v[18:21], v[236:239], v[204:207], v[150:153]
	v_mfma_f32_16x16x32_bf16 v[6:9], v[212:215], v[224:227], v[6:9]
	v_mfma_f32_16x16x32_bf16 v[2:5], v[236:239], v[224:227], v[2:5]
	v_mfma_f32_16x16x32_bf16 v[18:21], v[240:243], v[220:223], v[18:21]
	v_mfma_f32_16x16x32_bf16 v[6:9], v[216:219], v[228:231], v[6:9]
	v_mfma_f32_16x16x32_bf16 v[2:5], v[240:243], v[228:231], v[2:5]
	s_setprio 0
	s_barrier
	s_and_saveexec_b64 s[14:15], s[6:7]
	s_cbranch_execz .LBB0_544
	s_barrier

; #define LDA(dst, b, h) for (int m = 0; m < 4; ++m) for (int k = 0; k < 2; ++k) \
;     dst[m][k] = *reinterpret_cast<const bf16x8*>((char*)SA(b, h) + lds_byte(wr * 64 + m * 16 + fr, k * 32 + fq * 8))
; #define LDB(dst, b, h) for (int n = 0; n < 2; ++n) for (int k = 0; k < 2; ++k) \
;     dst[n][k] = *reinterpret_cast<const bf16x8*>((char*)SB(b, h) + lds_byte(wc * 32 + n * 16 + fr, k * 32 + fq * 8))
; #define WAIT_V(n) asm volatile("s_waitcnt vmcnt(" #n ")" ::: "memory")
; #define BAR __builtin_amdgcn_s_barrier()
; #define SCHED __builtin_amdgcn_sched_barrier(0)
; #define TILE_COORDS(wg, pm_, pn_) do { constexpr int WGM = 8; const int nig = WGM * nN, gid = (wg) / nig, fm = gid * WGM, gsz = min(nM - fm, WGM); \
;     pm_ = fm + (((wg) % nig) % gsz); pn_ = ((wg) % nig) / gsz; } while (0)
; template <int EPI> ...
;     ...
;     int pm, pn; TILE_COORDS(wgid, pm, pn);
;     const int brow = pm * BM, bcol = pn * BM;
;     f32x4 acc[2][2][4][2] = {};
;     bf16x8 At[4][2], B0[2][2], B1[2][2];
;     if (wr == 1) BAR;
;     WAIT_V(0); BAR;
;     STAGE(SB(1, 0), Bt, bcol, 1); STAGE(SA(1, 0), A, brow, 1); STAGE(SB(1, 1), Bt, bcol + HALF, 1);
;     WAIT_V(6); BAR;
;     for (int t = 0; t < nt - 2; t += 2) {
;       LDB(B0, 0, 0); SCHED; LDA(At, 0, 0); STAGE(SA(1, 1), A, brow + HALF, t + 1);
.LBB0_575:
	s_or_b64 exec, exec, s[16:17]
	s_ashr_i32 s16, s24, 31
	s_lshr_b32 s16, s16, 25
	s_add_i32 s16, s24, s16
	s_ashr_i32 s17, s16, 7
	s_and_b32 s16, s16, 0xff80
	s_sub_i32 s16, s24, s16
	s_lshl_b32 s22, s17, 3
	s_bfe_i32 s17, s16, 0x80000
	s_bfe_u32 s17, s17, 0x3000c
	s_add_i32 s17, s16, s17
	s_bfe_i32 s18, s17, 0x80000
	s_sext_i32_i16 s18, s18
	s_and_b32 s17, s17, 0xf8
	s_ashr_i32 s23, s18, 3
	s_sub_i32 s16, s16, s17
	s_lshl_b32 s18, s23, 1
	s_sext_i32_i8 s16, s16
	s_ashr_i32 s19, s18, 31
	s_add_i32 s22, s22, s16
	s_lshl_b64 s[16:17], s[18:19], 20
	s_add_u32 s25, s8, s16
	s_addc_u32 s26, s9, s17
	s_add_u32 s16, s25, 0x4000
	v_add_u32_e32 v0, s46, v148
	s_addc_u32 s17, s26, 0
	v_readfirstlane_b32 s19, v0
	s_waitcnt vmcnt(0)
	s_barrier
	s_mov_b32 m0, s19
	s_waitcnt lgkmcnt(0)
	v_lshl_add_u64 v[2:3], s[16:17], 0, v[148:149]
	v_add_u32_e32 v130, 0x2000, v0
	global_load_lds_dwordx4 v[2:3], off
	v_lshl_add_u64 v[2:3], s[16:17], 0, v[150:151]
	v_readfirstlane_b32 s16, v130
	s_mov_b32 m0, s16
	s_lshl_b32 s16, s22, 1
	s_ashr_i32 s17, s16, 31
	s_lshl_b64 s[28:29], s[16:17], 20
	s_add_u32 s17, s10, s28
	s_addc_u32 s27, s11, s29
	s_add_u32 s28, s17, 0x4000
	v_add_u32_e32 v131, 0x8000, v167
	s_addc_u32 s29, s27, 0
	v_readfirstlane_b32 s19, v131
	v_add_u32_e32 v132, 0xa000, v167
	global_load_lds_dwordx4 v[2:3], off
	s_mov_b32 m0, s19
	v_lshl_add_u64 v[2:3], s[28:29], 0, v[148:149]
	v_readfirstlane_b32 s19, v132
	s_or_b32 s18, s18, 1
	global_load_lds_dwordx4 v[2:3], off
	s_mov_b32 m0, s19
	s_ashr_i32 s19, s18, 31
	s_lshl_b64 s[18:19], s[18:19], 20
	s_add_u32 s18, s8, s18
	s_addc_u32 s19, s9, s19
	s_add_u32 s18, s18, 0x4000
	v_add_u32_e32 v133, s91, v148
	v_lshl_add_u64 v[2:3], s[28:29], 0, v[150:151]
	s_addc_u32 s19, s19, 0
	v_readfirstlane_b32 s28, v133
	global_load_lds_dwordx4 v[2:3], off
	s_mov_b32 m0, s28
	v_lshl_add_u64 v[2:3], s[18:19], 0, v[148:149]
	v_add_u32_e32 v134, 0x2000, v133
	global_load_lds_dwordx4 v[2:3], off
	v_lshl_add_u64 v[2:3], s[18:19], 0, v[150:151]
	v_readfirstlane_b32 s18, v134
	s_mov_b32 m0, s18
	s_mov_b32 s28, -2
	global_load_lds_dwordx4 v[2:3], off
	s_waitcnt vmcnt(6)
	v_mov_b32_e32 v2, 0
	s_mov_b64 s[18:19], 0
	v_mov_b32_e32 v3, v2
	v_mov_b32_e32 v4, v2
	v_mov_b32_e32 v5, v2
	v_mov_b32_e32 v6, v2
	v_mov_b32_e32 v7, v2
	v_mov_b32_e32 v8, v2
	v_mov_b32_e32 v9, v2
	v_mov_b32_e32 v10, v2
	v_mov_b32_e32 v11, v2
	v_mov_b32_e32 v12, v2
	v_mov_b32_e32 v13, v2
	v_mov_b32_e32 v14, v2
	v_mov_b32_e32 v15, v2
	v_mov_b32_e32 v16, v2
	v_mov_b32_e32 v17, v2
	v_mov_b32_e32 v18, v2
	v_mov_b32_e32 v19, v2
	v_mov_b32_e32 v20, v2
	v_mov_b32_e32 v21, v2
	v_mov_b32_e32 v22, v2
	v_mov_b32_e32 v23, v2
	v_mov_b32_e32 v24, v2
	v_mov_b32_e32 v25, v2
	v_mov_b32_e32 v26, v2
	v_mov_b32_e32 v27, v2
	v_mov_b32_e32 v28, v2
	v_mov_b32_e32 v29, v2
	v_mov_b32_e32 v30, v2
	v_mov_b32_e32 v31, v2
	v_mov_b32_e32 v32, v2
	v_mov_b32_e32 v33, v2
	v_mov_b32_e32 v34, v2
	v_mov_b32_e32 v35, v2
	v_mov_b32_e32 v36, v2
	v_mov_b32_e32 v37, v2
	v_mov_b32_e32 v38, v2
	v_mov_b32_e32 v39, v2
	v_mov_b32_e32 v40, v2
	v_mov_b32_e32 v41, v2
	v_mov_b32_e32 v42, v2
	v_mov_b32_e32 v43, v2
	v_mov_b32_e32 v44, v2
	v_mov_b32_e32 v45, v2
	v_mov_b32_e32 v46, v2
	v_mov_b32_e32 v47, v2
	v_mov_b32_e32 v48, v2
	v_mov_b32_e32 v49, v2
	v_mov_b32_e32 v50, v2
	v_mov_b32_e32 v51, v2
	v_mov_b32_e32 v52, v2
	v_mov_b32_e32 v53, v2
	v_mov_b32_e32 v54, v2
	v_mov_b32_e32 v55, v2
	v_mov_b32_e32 v56, v2
	v_mov_b32_e32 v57, v2
	v_mov_b32_e32 v58, v2
	v_mov_b32_e32 v59, v2
	v_mov_b32_e32 v60, v2
	v_mov_b32_e32 v61, v2
	v_mov_b32_e32 v62, v2
	v_mov_b32_e32 v63, v2
	v_mov_b32_e32 v64, v2
	v_mov_b32_e32 v65, v2
	v_mov_b32_e32 v66, v2
	v_mov_b32_e32 v67, v2
	v_mov_b32_e32 v68, v2
	v_mov_b32_e32 v69, v2
	v_mov_b32_e32 v70, v2
	v_mov_b32_e32 v71, v2
	v_mov_b32_e32 v72, v2
	v_mov_b32_e32 v73, v2
	v_mov_b32_e32 v74, v2
	v_mov_b32_e32 v75, v2
	v_mov_b32_e32 v76, v2
	v_mov_b32_e32 v77, v2
	v_mov_b32_e32 v78, v2
	v_mov_b32_e32 v79, v2
	v_mov_b32_e32 v80, v2
	v_mov_b32_e32 v81, v2
	v_mov_b32_e32 v82, v2
	v_mov_b32_e32 v83, v2
	v_mov_b32_e32 v84, v2
	v_mov_b32_e32 v85, v2
	v_mov_b32_e32 v86, v2
	v_mov_b32_e32 v87, v2
	v_mov_b32_e32 v88, v2
	v_mov_b32_e32 v89, v2
	v_mov_b32_e32 v90, v2
	v_mov_b32_e32 v91, v2
	v_mov_b32_e32 v92, v2
	v_mov_b32_e32 v93, v2
	v_mov_b32_e32 v94, v2
	v_mov_b32_e32 v95, v2
	v_mov_b32_e32 v96, v2
	v_mov_b32_e32 v97, v2
	v_mov_b32_e32 v98, v2
	v_mov_b32_e32 v99, v2
	v_mov_b32_e32 v100, v2
	v_mov_b32_e32 v101, v2
	v_mov_b32_e32 v102, v2
	v_mov_b32_e32 v103, v2
	v_mov_b32_e32 v104, v2
	v_mov_b32_e32 v105, v2
	v_mov_b32_e32 v106, v2
	v_mov_b32_e32 v107, v2
	v_mov_b32_e32 v108, v2
	v_mov_b32_e32 v109, v2
	v_mov_b32_e32 v110, v2
	v_mov_b32_e32 v111, v2
	v_mov_b32_e32 v112, v2
	v_mov_b32_e32 v113, v2
	v_mov_b32_e32 v114, v2
	v_mov_b32_e32 v115, v2
	v_mov_b32_e32 v116, v2
	v_mov_b32_e32 v117, v2
	v_mov_b32_e32 v118, v2
	v_mov_b32_e32 v119, v2
	v_mov_b32_e32 v120, v2
	v_mov_b32_e32 v121, v2
	v_mov_b32_e32 v122, v2
	v_mov_b32_e32 v123, v2
	v_mov_b32_e32 v124, v2
	v_mov_b32_e32 v125, v2
	v_mov_b32_e32 v126, v2
	v_mov_b32_e32 v127, v2
	v_mov_b32_e32 v128, v2
	v_mov_b32_e32 v129, v2
	s_barrier
	v_readfirstlane_b32 s32, v167
	v_add_u32_e32 v135, 0xc000, v167
	v_add_u32_e32 v136, 0xe000, v167
	v_add_u32_e32 v152, 0x2000, v168
	v_add_u32_e32 v153, 0x2000, v170
	ds_read_b128 v[138:141], v173
	ds_read_b128 v[142:145], v173 offset:1024
	ds_read_b128 v[154:157], v173 offset:2048
	ds_read_b128 v[158:161], v173 offset:3072
; #define LDA(dst, b, h) for (int m = 0; m < 4; ++m) for (int k = 0; k < 2; ++k) \
;     dst[m][k] = *reinterpret_cast<const bf16x8*>((char*)SA(b, h) + lds_byte(wr * 64 + m * 16 + fr, k * 32 + fq * 8))
; #define LDB(dst, b, h) for (int n = 0; n < 2; ++n) for (int k = 0; k < 2; ++k) \
;     dst[n][k] = *reinterpret_cast<const bf16x8*>((char*)SB(b, h) + lds_byte(wc * 32 + n * 16 + fr, k * 32 + fq * 8))
; #define MMA(ai, bj, At, Bt_) do { __builtin_amdgcn_s_setprio(1); \
;     for (int m = 0; m < 4; ++m) for (int n = 0; n < 2; ++n) for (int k = 0; k < 2; ++k) \
;       acc[ai][bj][m][n] = __builtin_amdgcn_mfma_f32_16x16x32_bf16(Bt_[n][k], At[m][k], acc[ai][bj][m][n], 0, 0, 0); \
;     __builtin_amdgcn_s_setprio(0); } while (0)
; #define WAIT_V(n) asm volatile("s_waitcnt vmcnt(" #n ")" ::: "memory")
; #define WAIT_L(n) asm volatile("s_waitcnt lgkmcnt(" #n ")" ::: "memory")
; #define BAR __builtin_amdgcn_s_barrier()
; #define SCHED __builtin_amdgcn_sched_barrier(0)
; template <int EPI> ...
;     ...
;       LDB(B0, 0, 0); SCHED; LDA(At, 0, 0); STAGE(SA(1, 1), A, brow + HALF, t + 1);
;       WAIT_L(8); BAR; WAIT_L(0); MMA(0, 0, At, B0); BAR; SCHED;
;       LDB(B1, 0, 1); STAGE(SB(0, 0), Bt, bcol, t + 2);
;       BAR; WAIT_L(0); MMA(0, 1, At, B1); BAR;
;       LDA(At, 0, 1); STAGE(SA(0, 0), A, brow, t + 2);
;       BAR; WAIT_L(0); MMA(1, 0, At, B0); BAR; SCHED;
;       STAGE(SB(0, 1), Bt, bcol + HALF, t + 2);
;       WAIT_V(6); BAR; MMA(1, 1, At, B1); BAR;
;       LDB(B0, 1, 0); SCHED; LDA(At, 1, 0); STAGE(SA(0, 1), A, brow + HALF, t + 2);
.LBB0_576:
	s_add_u32 s29, s17, s18
	s_addc_u32 s30, s27, s19
	s_add_u32 s34, s29, 0x104000
	s_addc_u32 s35, s30, 0
	ds_read_b128 v[162:165], v174
	ds_read_b128 v[182:185], v174 offset:1024
	ds_read_b128 v[186:189], v175
	ds_read_b128 v[200:203], v175 offset:1024
	ds_read_b128 v[204:207], v176
	ds_read_b128 v[208:211], v176 offset:1024
	ds_read_b128 v[212:215], v177
	ds_read_b128 v[216:219], v177 offset:1024
	s_add_u32 m0, s32, 0xc000
	s_nop 0
	global_load_lds_dwordx4 v148, s[34:35]
	s_add_u32 m0, s32, 0xe000
	s_nop 0
	global_load_lds_dwordx4 v150, s[34:35]
	s_waitcnt lgkmcnt(8)
	s_barrier
	s_waitcnt lgkmcnt(0)
	s_setprio 1
	s_waitcnt lgkmcnt(0)
	v_mfma_f32_16x16x32_bf16 v[126:129], v[138:141], v[162:165], v[126:129]
	v_mfma_f32_16x16x32_bf16 v[122:125], v[154:157], v[162:165], v[122:125]
	v_mfma_f32_16x16x32_bf16 v[118:121], v[138:141], v[186:189], v[118:121]
	v_mfma_f32_16x16x32_bf16 v[114:117], v[154:157], v[186:189], v[114:117]
	v_mfma_f32_16x16x32_bf16 v[110:113], v[138:141], v[204:207], v[110:113]
	v_mfma_f32_16x16x32_bf16 v[106:109], v[154:157], v[204:207], v[106:109]
	v_mfma_f32_16x16x32_bf16 v[102:105], v[138:141], v[212:215], v[102:105]
	v_mfma_f32_16x16x32_bf16 v[98:101], v[154:157], v[212:215], v[98:101]
	v_mfma_f32_16x16x32_bf16 v[126:129], v[142:145], v[182:185], v[126:129]
	v_mfma_f32_16x16x32_bf16 v[122:125], v[158:161], v[182:185], v[122:125]
	v_mfma_f32_16x16x32_bf16 v[118:121], v[142:145], v[200:203], v[118:121]
	v_mfma_f32_16x16x32_bf16 v[114:117], v[158:161], v[200:203], v[114:117]
	v_mfma_f32_16x16x32_bf16 v[110:113], v[142:145], v[208:211], v[110:113]
	v_mfma_f32_16x16x32_bf16 v[106:109], v[158:161], v[208:211], v[106:109]
	v_mfma_f32_16x16x32_bf16 v[102:105], v[142:145], v[216:219], v[102:105]
	v_mfma_f32_16x16x32_bf16 v[98:101], v[158:161], v[216:219], v[98:101]
	s_setprio 0
	s_barrier
	s_add_u32 s31, s25, s18
	s_addc_u32 s34, s26, s19
	s_add_u32 s36, s31, 0x8000
	s_addc_u32 s37, s34, 0
	ds_read_b128 v[220:223], v178
	ds_read_b128 v[224:227], v178 offset:1024
	ds_read_b128 v[228:231], v178 offset:2048
	ds_read_b128 v[232:235], v178 offset:3072
	s_add_u32 m0, s32, 0x10000
	s_nop 0
	global_load_lds_dwordx4 v148, s[36:37]
	s_add_u32 m0, s32, 0x12000
	s_nop 0
	global_load_lds_dwordx4 v150, s[36:37]
	s_barrier
	s_waitcnt lgkmcnt(0)
	s_setprio 1
	s_waitcnt lgkmcnt(0)
	v_mfma_f32_16x16x32_bf16 v[94:97], v[220:223], v[162:165], v[94:97]
	v_mfma_f32_16x16x32_bf16 v[90:93], v[228:231], v[162:165], v[90:93]
	v_mfma_f32_16x16x32_bf16 v[86:89], v[220:223], v[186:189], v[86:89]
	v_mfma_f32_16x16x32_bf16 v[82:85], v[228:231], v[186:189], v[82:85]
	v_mfma_f32_16x16x32_bf16 v[78:81], v[220:223], v[204:207], v[78:81]
	v_mfma_f32_16x16x32_bf16 v[74:77], v[228:231], v[204:207], v[74:77]
	v_mfma_f32_16x16x32_bf16 v[70:73], v[220:223], v[212:215], v[70:73]
	v_mfma_f32_16x16x32_bf16 v[66:69], v[228:231], v[212:215], v[66:69]
	v_mfma_f32_16x16x32_bf16 v[94:97], v[224:227], v[182:185], v[94:97]
	v_mfma_f32_16x16x32_bf16 v[90:93], v[232:235], v[182:185], v[90:93]
	v_mfma_f32_16x16x32_bf16 v[86:89], v[224:227], v[200:203], v[86:89]
	v_mfma_f32_16x16x32_bf16 v[82:85], v[232:235], v[200:203], v[82:85]
	v_mfma_f32_16x16x32_bf16 v[78:81], v[224:227], v[208:211], v[78:81]
	v_mfma_f32_16x16x32_bf16 v[74:77], v[232:235], v[208:211], v[74:77]
	v_mfma_f32_16x16x32_bf16 v[70:73], v[224:227], v[216:219], v[70:73]
	v_mfma_f32_16x16x32_bf16 v[66:69], v[232:235], v[216:219], v[66:69]
	s_setprio 0
	s_add_u32 s36, s29, 0x8000
	s_addc_u32 s37, s30, 0
	s_barrier
	ds_read_b128 v[162:165], v174 offset:16384
	ds_read_b128 v[182:185], v174 offset:17408
	ds_read_b128 v[186:189], v175 offset:16384
	ds_read_b128 v[200:203], v175 offset:17408
	ds_read_b128 v[204:207], v176 offset:16384
	ds_read_b128 v[208:211], v176 offset:17408
	ds_read_b128 v[212:215], v177 offset:16384
	ds_read_b128 v[216:219], v177 offset:17408
	s_add_u32 m0, s32, 0x0
	s_nop 0
	global_load_lds_dwordx4 v148, s[36:37]
	s_add_u32 m0, s32, 0x2000
	s_nop 0
	global_load_lds_dwordx4 v150, s[36:37]
	s_waitcnt vmcnt(10)
	s_barrier
	s_waitcnt lgkmcnt(0)
	s_setprio 1
	s_waitcnt lgkmcnt(0)
	v_mfma_f32_16x16x32_bf16 v[62:65], v[138:141], v[162:165], v[62:65]
	v_mfma_f32_16x16x32_bf16 v[58:61], v[154:157], v[162:165], v[58:61]
	v_mfma_f32_16x16x32_bf16 v[54:57], v[138:141], v[186:189], v[54:57]
	v_mfma_f32_16x16x32_bf16 v[50:53], v[154:157], v[186:189], v[50:53]
	v_mfma_f32_16x16x32_bf16 v[46:49], v[138:141], v[204:207], v[46:49]
	v_mfma_f32_16x16x32_bf16 v[42:45], v[154:157], v[204:207], v[42:45]
	v_mfma_f32_16x16x32_bf16 v[38:41], v[138:141], v[212:215], v[38:41]
	v_mfma_f32_16x16x32_bf16 v[34:37], v[154:157], v[212:215], v[34:37]
	v_mfma_f32_16x16x32_bf16 v[62:65], v[142:145], v[182:185], v[62:65]
	v_mfma_f32_16x16x32_bf16 v[58:61], v[158:161], v[182:185], v[58:61]
	v_mfma_f32_16x16x32_bf16 v[54:57], v[142:145], v[200:203], v[54:57]
	v_mfma_f32_16x16x32_bf16 v[50:53], v[158:161], v[200:203], v[50:53]
	v_mfma_f32_16x16x32_bf16 v[46:49], v[142:145], v[208:211], v[46:49]
	v_mfma_f32_16x16x32_bf16 v[42:45], v[158:161], v[208:211], v[42:45]
	v_mfma_f32_16x16x32_bf16 v[38:41], v[142:145], v[216:219], v[38:41]
	v_mfma_f32_16x16x32_bf16 v[34:37], v[158:161], v[216:219], v[34:37]
	s_setprio 0
	s_barrier
	ds_read_b128 v[138:141], v179
	ds_read_b128 v[142:145], v179 offset:1024
	ds_read_b128 v[154:157], v179 offset:2048
	ds_read_b128 v[158:161], v179 offset:3072
	s_add_u32 s36, s31, 0x108000
	s_addc_u32 s37, s34, 0
	s_add_u32 m0, s32, 0x14000
	s_nop 0
	global_load_lds_dwordx4 v148, s[36:37]
	s_add_u32 m0, s32, 0x16000
	s_nop 0
	global_load_lds_dwordx4 v150, s[36:37]
	s_waitcnt vmcnt(6)
	s_barrier
; #define LDA(dst, b, h) for (int m = 0; m < 4; ++m) for (int k = 0; k < 2; ++k) \
;     dst[m][k] = *reinterpret_cast<const bf16x8*>((char*)SA(b, h) + lds_byte(wr * 64 + m * 16 + fr, k * 32 + fq * 8))
; #define LDB(dst, b, h) for (int n = 0; n < 2; ++n) for (int k = 0; k < 2; ++k) \
;     dst[n][k] = *reinterpret_cast<const bf16x8*>((char*)SB(b, h) + lds_byte(wc * 32 + n * 16 + fr, k * 32 + fq * 8))
; #define MMA(ai, bj, At, Bt_) do { __builtin_amdgcn_s_setprio(1); \
;     for (int m = 0; m < 4; ++m) for (int n = 0; n < 2; ++n) for (int k = 0; k < 2; ++k) \
;       acc[ai][bj][m][n] = __builtin_amdgcn_mfma_f32_16x16x32_bf16(Bt_[n][k], At[m][k], acc[ai][bj][m][n], 0, 0, 0); \
;     __builtin_amdgcn_s_setprio(0); } while (0)
; #define WAIT_V(n) asm volatile("s_waitcnt vmcnt(" #n ")" ::: "memory")
; #define WAIT_L(n) asm volatile("s_waitcnt lgkmcnt(" #n ")" ::: "memory")
; #define BAR __builtin_amdgcn_s_barrier()
; #define SCHED __builtin_amdgcn_sched_barrier(0)
; template <int EPI> ...
;     ...
;       WAIT_V(6); BAR; MMA(1, 1, At, B1); BAR;
;       LDB(B0, 1, 0); SCHED; LDA(At, 1, 0); STAGE(SA(0, 1), A, brow + HALF, t + 2);
;       WAIT_L(8); BAR; WAIT_L(0); MMA(0, 0, At, B0); BAR; SCHED;
;       LDB(B1, 1, 1); STAGE(SB(1, 0), Bt, bcol, t + 3);
;       BAR; WAIT_L(0); MMA(0, 1, At, B1); BAR;
;       LDA(At, 1, 1); STAGE(SA(1, 0), A, brow, t + 3);
;       BAR; WAIT_L(0); MMA(1, 0, At, B0); BAR; SCHED;
	s_setprio 1
	v_mfma_f32_16x16x32_bf16 v[30:33], v[220:223], v[162:165], v[30:33]
	v_mfma_f32_16x16x32_bf16 v[26:29], v[228:231], v[162:165], v[26:29]
	v_mfma_f32_16x16x32_bf16 v[22:25], v[220:223], v[186:189], v[22:25]
	v_mfma_f32_16x16x32_bf16 v[18:21], v[228:231], v[186:189], v[18:21]
	v_mfma_f32_16x16x32_bf16 v[14:17], v[220:223], v[204:207], v[14:17]
	v_mfma_f32_16x16x32_bf16 v[10:13], v[228:231], v[204:207], v[10:13]
	v_mfma_f32_16x16x32_bf16 v[6:9], v[220:223], v[212:215], v[6:9]
	v_mfma_f32_16x16x32_bf16 v[2:5], v[228:231], v[212:215], v[2:5]
	v_mfma_f32_16x16x32_bf16 v[30:33], v[224:227], v[182:185], v[30:33]
	v_mfma_f32_16x16x32_bf16 v[26:29], v[232:235], v[182:185], v[26:29]
	v_mfma_f32_16x16x32_bf16 v[22:25], v[224:227], v[200:203], v[22:25]
	v_mfma_f32_16x16x32_bf16 v[18:21], v[232:235], v[200:203], v[18:21]
	v_mfma_f32_16x16x32_bf16 v[14:17], v[224:227], v[208:211], v[14:17]
	v_mfma_f32_16x16x32_bf16 v[10:13], v[232:235], v[208:211], v[10:13]
	v_mfma_f32_16x16x32_bf16 v[6:9], v[224:227], v[216:219], v[6:9]
	v_mfma_f32_16x16x32_bf16 v[2:5], v[232:235], v[216:219], v[2:5]
	s_setprio 0
	s_barrier
	s_add_u32 s36, s29, 0x108000
	s_addc_u32 s37, s30, 0
	ds_read_b128 v[162:165], v174 offset:32768
	ds_read_b128 v[182:185], v174 offset:33792
	ds_read_b128 v[186:189], v175 offset:32768
	ds_read_b128 v[200:203], v175 offset:33792
	ds_read_b128 v[204:207], v176 offset:32768
	ds_read_b128 v[208:211], v176 offset:33792
	ds_read_b128 v[212:215], v177 offset:32768
	ds_read_b128 v[216:219], v177 offset:33792
	s_add_u32 m0, s32, 0x4000
	s_nop 0
	global_load_lds_dwordx4 v148, s[36:37]
	s_add_u32 m0, s32, 0x6000
	s_nop 0
	global_load_lds_dwordx4 v150, s[36:37]
	s_waitcnt lgkmcnt(8)
	s_barrier
	s_waitcnt lgkmcnt(0)
	s_setprio 1
	s_waitcnt lgkmcnt(0)
	v_mfma_f32_16x16x32_bf16 v[126:129], v[138:141], v[162:165], v[126:129]
	v_mfma_f32_16x16x32_bf16 v[122:125], v[154:157], v[162:165], v[122:125]
	v_mfma_f32_16x16x32_bf16 v[118:121], v[138:141], v[186:189], v[118:121]
	v_mfma_f32_16x16x32_bf16 v[114:117], v[154:157], v[186:189], v[114:117]
	v_mfma_f32_16x16x32_bf16 v[110:113], v[138:141], v[204:207], v[110:113]
	v_mfma_f32_16x16x32_bf16 v[106:109], v[154:157], v[204:207], v[106:109]
	v_mfma_f32_16x16x32_bf16 v[102:105], v[138:141], v[212:215], v[102:105]
	v_mfma_f32_16x16x32_bf16 v[98:101], v[154:157], v[212:215], v[98:101]
	v_mfma_f32_16x16x32_bf16 v[126:129], v[142:145], v[182:185], v[126:129]
	v_mfma_f32_16x16x32_bf16 v[122:125], v[158:161], v[182:185], v[122:125]
	v_mfma_f32_16x16x32_bf16 v[118:121], v[142:145], v[200:203], v[118:121]
	v_mfma_f32_16x16x32_bf16 v[114:117], v[158:161], v[200:203], v[114:117]
	v_mfma_f32_16x16x32_bf16 v[110:113], v[142:145], v[208:211], v[110:113]
	v_mfma_f32_16x16x32_bf16 v[106:109], v[158:161], v[208:211], v[106:109]
	v_mfma_f32_16x16x32_bf16 v[102:105], v[142:145], v[216:219], v[102:105]
	v_mfma_f32_16x16x32_bf16 v[98:101], v[158:161], v[216:219], v[98:101]
	s_setprio 0
	s_barrier
	s_add_u32 s36, s31, 0xc000
	s_addc_u32 s37, s34, 0
	ds_read_b128 v[220:223], v180
	ds_read_b128 v[224:227], v180 offset:1024
	ds_read_b128 v[228:231], v180 offset:2048
	ds_read_b128 v[232:235], v180 offset:3072
	s_add_u32 m0, s32, 0x18000
	s_nop 0
	global_load_lds_dwordx4 v148, s[36:37]
	s_add_u32 m0, s32, 0x1a000
	s_nop 0
	global_load_lds_dwordx4 v150, s[36:37]
	s_barrier
	s_waitcnt lgkmcnt(0)
	s_setprio 1
	s_waitcnt lgkmcnt(0)
	v_mfma_f32_16x16x32_bf16 v[94:97], v[220:223], v[162:165], v[94:97]
	v_mfma_f32_16x16x32_bf16 v[90:93], v[228:231], v[162:165], v[90:93]
	v_mfma_f32_16x16x32_bf16 v[86:89], v[220:223], v[186:189], v[86:89]
	v_mfma_f32_16x16x32_bf16 v[82:85], v[228:231], v[186:189], v[82:85]
	v_mfma_f32_16x16x32_bf16 v[78:81], v[220:223], v[204:207], v[78:81]
	v_mfma_f32_16x16x32_bf16 v[74:77], v[228:231], v[204:207], v[74:77]
	v_mfma_f32_16x16x32_bf16 v[70:73], v[220:223], v[212:215], v[70:73]
	v_mfma_f32_16x16x32_bf16 v[66:69], v[228:231], v[212:215], v[66:69]
	v_mfma_f32_16x16x32_bf16 v[94:97], v[224:227], v[182:185], v[94:97]
	v_mfma_f32_16x16x32_bf16 v[90:93], v[232:235], v[182:185], v[90:93]
	v_mfma_f32_16x16x32_bf16 v[86:89], v[224:227], v[200:203], v[86:89]
	v_mfma_f32_16x16x32_bf16 v[82:85], v[232:235], v[200:203], v[82:85]
	v_mfma_f32_16x16x32_bf16 v[78:81], v[224:227], v[208:211], v[78:81]
	v_mfma_f32_16x16x32_bf16 v[74:77], v[232:235], v[208:211], v[74:77]
	v_mfma_f32_16x16x32_bf16 v[70:73], v[224:227], v[216:219], v[70:73]
	v_mfma_f32_16x16x32_bf16 v[66:69], v[232:235], v[216:219], v[66:69]
	s_setprio 0
	s_add_u32 s36, s29, 0xc000
	s_addc_u32 s37, s30, 0
	s_barrier
	ds_read_b128 v[162:165], v174 offset:49152
	ds_read_b128 v[182:185], v174 offset:50176
	ds_read_b128 v[186:189], v175 offset:49152
	ds_read_b128 v[200:203], v175 offset:50176
	ds_read_b128 v[204:207], v176 offset:49152
	ds_read_b128 v[208:211], v176 offset:50176
	ds_read_b128 v[212:215], v177 offset:49152
	ds_read_b128 v[216:219], v177 offset:50176
	s_add_u32 m0, s32, 0x8000
	s_nop 0
	global_load_lds_dwordx4 v148, s[36:37]
	s_add_u32 m0, s32, 0xa000
	s_nop 0
	global_load_lds_dwordx4 v150, s[36:37]
	s_waitcnt vmcnt(10)
	s_barrier
; #define LDA(dst, b, h) for (int m = 0; m < 4; ++m) for (int k = 0; k < 2; ++k) \
;     dst[m][k] = *reinterpret_cast<const bf16x8*>((char*)SA(b, h) + lds_byte(wr * 64 + m * 16 + fr, k * 32 + fq * 8))
; #define LDB(dst, b, h) for (int n = 0; n < 2; ++n) for (int k = 0; k < 2; ++k) \
;     dst[n][k] = *reinterpret_cast<const bf16x8*>((char*)SB(b, h) + lds_byte(wc * 32 + n * 16 + fr, k * 32 + fq * 8))
; #define MMA(ai, bj, At, Bt_) do { __builtin_amdgcn_s_setprio(1); \
;     for (int m = 0; m < 4; ++m) for (int n = 0; n < 2; ++n) for (int k = 0; k < 2; ++k) \
;       acc[ai][bj][m][n] = __builtin_amdgcn_mfma_f32_16x16x32_bf16(Bt_[n][k], At[m][k], acc[ai][bj][m][n], 0, 0, 0); \
;     __builtin_amdgcn_s_setprio(0); } while (0)
; #define WAIT_V(n) asm volatile("s_waitcnt vmcnt(" #n ")" ::: "memory")
; #define WAIT_L(n) asm volatile("s_waitcnt lgkmcnt(" #n ")" ::: "memory")
; #define BAR __builtin_amdgcn_s_barrier()
; #define SCHED __builtin_amdgcn_sched_barrier(0)
; template <int EPI> ...
;     ...
;       BAR; WAIT_L(0); MMA(1, 0, At, B0); BAR; SCHED;
;       STAGE(SB(1, 1), Bt, bcol + HALF, t + 3);
;       WAIT_V(6); BAR; MMA(1, 1, At, B1); BAR;
;     }
;     { LDB(B0, 0, 0); LDA(At, 0, 0); STAGE(SA(1, 1), A, brow + HALF, nt - 1);
;       BAR; WAIT_L(0); MMA(0, 0, At, B0); BAR;
;       LDB(B1, 0, 1); BAR; WAIT_L(0); MMA(0, 1, At, B1); BAR;
	s_waitcnt lgkmcnt(0)
	s_setprio 1
	s_waitcnt lgkmcnt(0)
	v_mfma_f32_16x16x32_bf16 v[62:65], v[138:141], v[162:165], v[62:65]
	v_mfma_f32_16x16x32_bf16 v[58:61], v[154:157], v[162:165], v[58:61]
	v_mfma_f32_16x16x32_bf16 v[54:57], v[138:141], v[186:189], v[54:57]
	v_mfma_f32_16x16x32_bf16 v[50:53], v[154:157], v[186:189], v[50:53]
	v_mfma_f32_16x16x32_bf16 v[46:49], v[138:141], v[204:207], v[46:49]
	v_mfma_f32_16x16x32_bf16 v[42:45], v[154:157], v[204:207], v[42:45]
	v_mfma_f32_16x16x32_bf16 v[38:41], v[138:141], v[212:215], v[38:41]
	v_mfma_f32_16x16x32_bf16 v[34:37], v[154:157], v[212:215], v[34:37]
	v_mfma_f32_16x16x32_bf16 v[62:65], v[142:145], v[182:185], v[62:65]
	v_mfma_f32_16x16x32_bf16 v[58:61], v[158:161], v[182:185], v[58:61]
	v_mfma_f32_16x16x32_bf16 v[54:57], v[142:145], v[200:203], v[54:57]
	v_mfma_f32_16x16x32_bf16 v[50:53], v[158:161], v[200:203], v[50:53]
	v_mfma_f32_16x16x32_bf16 v[46:49], v[142:145], v[208:211], v[46:49]
	v_mfma_f32_16x16x32_bf16 v[42:45], v[158:161], v[208:211], v[42:45]
	v_mfma_f32_16x16x32_bf16 v[38:41], v[142:145], v[216:219], v[38:41]
	v_mfma_f32_16x16x32_bf16 v[34:37], v[158:161], v[216:219], v[34:37]
	s_setprio 0
	s_barrier
	ds_read_b128 v[138:141], v173
	ds_read_b128 v[142:145], v173 offset:1024
	ds_read_b128 v[154:157], v173 offset:2048
	ds_read_b128 v[158:161], v173 offset:3072
	s_add_u32 s30, s31, 0x10c000
	s_addc_u32 s31, s34, 0
	s_add_u32 m0, s32, 0x1c000
	s_nop 0
	global_load_lds_dwordx4 v148, s[30:31]
	s_add_u32 m0, s32, 0x1e000
	s_nop 0
	global_load_lds_dwordx4 v150, s[30:31]
	s_waitcnt vmcnt(6)
	s_barrier
	s_setprio 1
	v_mfma_f32_16x16x32_bf16 v[30:33], v[220:223], v[162:165], v[30:33]
	v_mfma_f32_16x16x32_bf16 v[26:29], v[228:231], v[162:165], v[26:29]
	v_mfma_f32_16x16x32_bf16 v[22:25], v[220:223], v[186:189], v[22:25]
	v_mfma_f32_16x16x32_bf16 v[18:21], v[228:231], v[186:189], v[18:21]
	v_mfma_f32_16x16x32_bf16 v[14:17], v[220:223], v[204:207], v[14:17]
	v_mfma_f32_16x16x32_bf16 v[10:13], v[228:231], v[204:207], v[10:13]
	v_mfma_f32_16x16x32_bf16 v[6:9], v[220:223], v[212:215], v[6:9]
	v_mfma_f32_16x16x32_bf16 v[2:5], v[228:231], v[212:215], v[2:5]
	v_mfma_f32_16x16x32_bf16 v[30:33], v[224:227], v[182:185], v[30:33]
	v_mfma_f32_16x16x32_bf16 v[26:29], v[232:235], v[182:185], v[26:29]
	v_mfma_f32_16x16x32_bf16 v[22:25], v[224:227], v[200:203], v[22:25]
	v_mfma_f32_16x16x32_bf16 v[18:21], v[232:235], v[200:203], v[18:21]
	v_mfma_f32_16x16x32_bf16 v[14:17], v[224:227], v[208:211], v[14:17]
	v_mfma_f32_16x16x32_bf16 v[10:13], v[232:235], v[208:211], v[10:13]
	v_mfma_f32_16x16x32_bf16 v[6:9], v[224:227], v[216:219], v[6:9]
	v_mfma_f32_16x16x32_bf16 v[2:5], v[232:235], v[216:219], v[2:5]
	s_setprio 0
	s_add_i32 s28, s28, 2
	s_add_u32 s18, s18, 0x8000
	s_addc_u32 s19, s19, 0
	s_cmp_lt_u32 s28, 60
	s_barrier
	s_cbranch_scc1 .LBB0_576
	s_or_b32 s16, s16, 1
	s_ashr_i32 s17, s16, 31
	s_lshl_b64 s[16:17], s[16:17], 20
	s_add_u32 s16, s10, s16
	s_addc_u32 s17, s11, s17
	s_add_u32 s16, s16, 0xfc000
	s_addc_u32 s17, s17, 0
	ds_read_b128 v[130:133], v173
	ds_read_b128 v[138:141], v173 offset:1024
	ds_read_b128 v[142:145], v173 offset:2048
	ds_read_b128 v[154:157], v173 offset:3072
	ds_read_b128 v[158:161], v174
	ds_read_b128 v[162:165], v174 offset:1024
	ds_read_b128 v[182:185], v175
	ds_read_b128 v[186:189], v175 offset:1024
	ds_read_b128 v[200:203], v176
	ds_read_b128 v[204:207], v176 offset:1024
	ds_read_b128 v[208:211], v177
	ds_read_b128 v[212:215], v177 offset:1024
	v_readfirstlane_b32 s18, v135
	v_lshl_add_u64 v[146:147], s[16:17], 0, v[148:149]
	s_mov_b32 m0, s18
	v_lshl_add_u64 v[134:135], s[16:17], 0, v[150:151]
	v_readfirstlane_b32 s16, v136
	global_load_lds_dwordx4 v[146:147], off
	s_mov_b32 m0, s16
	s_nop 0
	global_load_lds_dwordx4 v[134:135], off
	s_barrier
	s_waitcnt lgkmcnt(0)
	s_setprio 1
	s_waitcnt lgkmcnt(0)
	v_mfma_f32_16x16x32_bf16 v[114:117], v[142:145], v[182:185], v[114:117]
	v_mfma_f32_16x16x32_bf16 v[110:113], v[130:133], v[200:203], v[110:113]
	v_mfma_f32_16x16x32_bf16 v[106:109], v[142:145], v[200:203], v[106:109]
	v_mfma_f32_16x16x32_bf16 v[98:101], v[142:145], v[208:211], v[98:101]
	v_mfma_f32_16x16x32_bf16 v[126:129], v[130:133], v[158:161], v[126:129]
	v_mfma_f32_16x16x32_bf16 v[122:125], v[142:145], v[158:161], v[122:125]
	v_mfma_f32_16x16x32_bf16 v[118:121], v[130:133], v[182:185], v[118:121]
	v_mfma_f32_16x16x32_bf16 v[114:117], v[154:157], v[186:189], v[114:117]
	v_mfma_f32_16x16x32_bf16 v[134:137], v[138:141], v[204:207], v[110:113]
	v_mfma_f32_16x16x32_bf16 v[106:109], v[154:157], v[204:207], v[106:109]
	v_mfma_f32_16x16x32_bf16 v[102:105], v[130:133], v[208:211], v[102:105]
	v_mfma_f32_16x16x32_bf16 v[98:101], v[154:157], v[212:215], v[98:101]
	v_mfma_f32_16x16x32_bf16 v[126:129], v[138:141], v[162:165], v[126:129]
	v_mfma_f32_16x16x32_bf16 v[122:125], v[154:157], v[162:165], v[122:125]
	v_mfma_f32_16x16x32_bf16 v[118:121], v[138:141], v[186:189], v[118:121]
	v_mfma_f32_16x16x32_bf16 v[216:219], v[138:141], v[212:215], v[102:105]
	s_setprio 0
	s_barrier
	s_nop 0
	ds_read_b128 v[102:105], v178
	ds_read_b128 v[110:113], v178 offset:1024
	ds_read_b128 v[220:223], v178 offset:2048
	ds_read_b128 v[224:227], v178 offset:3072
	s_barrier
; #define LDA(dst, b, h) for (int m = 0; m < 4; ++m) for (int k = 0; k < 2; ++k) \
;     dst[m][k] = *reinterpret_cast<const bf16x8*>((char*)SA(b, h) + lds_byte(wr * 64 + m * 16 + fr, k * 32 + fq * 8))
; #define LDB(dst, b, h) for (int n = 0; n < 2; ++n) for (int k = 0; k < 2; ++k) \
;     dst[n][k] = *reinterpret_cast<const bf16x8*>((char*)SB(b, h) + lds_byte(wc * 32 + n * 16 + fr, k * 32 + fq * 8))
; #define MMA(ai, bj, At, Bt_) do { __builtin_amdgcn_s_setprio(1); \
;     for (int m = 0; m < 4; ++m) for (int n = 0; n < 2; ++n) for (int k = 0; k < 2; ++k) \
;       acc[ai][bj][m][n] = __builtin_amdgcn_mfma_f32_16x16x32_bf16(Bt_[n][k], At[m][k], acc[ai][bj][m][n], 0, 0, 0); \
;     __builtin_amdgcn_s_setprio(0); } while (0)
; #define WAIT_V(n) asm volatile("s_waitcnt vmcnt(" #n ")" ::: "memory")
; #define WAIT_L(n) asm volatile("s_waitcnt lgkmcnt(" #n ")" ::: "memory")
; #define BAR __builtin_amdgcn_s_barrier()
; template <int EPI> ...
;     ...
;       LDB(B1, 0, 1); BAR; WAIT_L(0); MMA(0, 1, At, B1); BAR;
;       LDA(At, 0, 1); WAIT_V(4); BAR; WAIT_L(0); MMA(1, 0, At, B0); MMA(1, 1, At, B1); BAR; }
;     { LDB(B0, 1, 0); LDA(At, 1, 0); WAIT_V(2); BAR; WAIT_L(0); MMA(0, 0, At, B0); BAR;
	s_waitcnt lgkmcnt(0)
	s_setprio 1
	s_waitcnt lgkmcnt(0)
	v_mfma_f32_16x16x32_bf16 v[86:89], v[102:105], v[182:185], v[86:89]
	v_mfma_f32_16x16x32_bf16 v[82:85], v[220:223], v[182:185], v[82:85]
	v_mfma_f32_16x16x32_bf16 v[74:77], v[220:223], v[200:203], v[74:77]
	v_mfma_f32_16x16x32_bf16 v[66:69], v[220:223], v[208:211], v[66:69]
	v_mfma_f32_16x16x32_bf16 v[94:97], v[102:105], v[158:161], v[94:97]
	v_mfma_f32_16x16x32_bf16 v[90:93], v[220:223], v[158:161], v[90:93]
	v_mfma_f32_16x16x32_bf16 v[86:89], v[110:113], v[186:189], v[86:89]
	v_mfma_f32_16x16x32_bf16 v[82:85], v[224:227], v[186:189], v[82:85]
	v_mfma_f32_16x16x32_bf16 v[78:81], v[102:105], v[200:203], v[78:81]
	v_mfma_f32_16x16x32_bf16 v[74:77], v[224:227], v[204:207], v[74:77]
	v_mfma_f32_16x16x32_bf16 v[70:73], v[102:105], v[208:211], v[70:73]
	v_mfma_f32_16x16x32_bf16 v[66:69], v[224:227], v[212:215], v[66:69]
	v_mfma_f32_16x16x32_bf16 v[228:231], v[110:113], v[162:165], v[94:97]
	v_mfma_f32_16x16x32_bf16 v[158:161], v[224:227], v[162:165], v[90:93]
	v_mfma_f32_16x16x32_bf16 v[162:165], v[110:113], v[204:207], v[78:81]
	v_mfma_f32_16x16x32_bf16 v[182:185], v[110:113], v[212:215], v[70:73]
	s_setprio 0
	s_barrier
	s_nop 0
	ds_read_b128 v[70:73], v174 offset:16384
	ds_read_b128 v[78:81], v174 offset:17408
	ds_read_b128 v[90:93], v175 offset:16384
	ds_read_b128 v[94:97], v175 offset:17408
	ds_read_b128 v[186:189], v176 offset:16384
	ds_read_b128 v[200:203], v176 offset:17408
	ds_read_b128 v[204:207], v177 offset:16384
	ds_read_b128 v[208:211], v177 offset:17408
	s_waitcnt vmcnt(4)
	s_barrier
	s_waitcnt lgkmcnt(0)
	s_setprio 1
	s_waitcnt lgkmcnt(0)
	v_mfma_f32_16x16x32_bf16 v[62:65], v[130:133], v[70:73], v[62:65]
	v_mfma_f32_16x16x32_bf16 v[58:61], v[142:145], v[70:73], v[58:61]
	v_mfma_f32_16x16x32_bf16 v[54:57], v[130:133], v[90:93], v[54:57]
	v_mfma_f32_16x16x32_bf16 v[50:53], v[142:145], v[90:93], v[50:53]
	v_mfma_f32_16x16x32_bf16 v[38:41], v[130:133], v[204:207], v[38:41]
	v_mfma_f32_16x16x32_bf16 v[34:37], v[142:145], v[204:207], v[34:37]
	v_mfma_f32_16x16x32_bf16 v[62:65], v[138:141], v[78:81], v[62:65]
	v_mfma_f32_16x16x32_bf16 v[58:61], v[154:157], v[78:81], v[58:61]
	v_mfma_f32_16x16x32_bf16 v[54:57], v[138:141], v[94:97], v[54:57]
	v_mfma_f32_16x16x32_bf16 v[50:53], v[154:157], v[94:97], v[50:53]
	v_mfma_f32_16x16x32_bf16 v[46:49], v[130:133], v[186:189], v[46:49]
	v_mfma_f32_16x16x32_bf16 v[42:45], v[142:145], v[186:189], v[42:45]
	v_mfma_f32_16x16x32_bf16 v[38:41], v[138:141], v[208:211], v[38:41]
	v_mfma_f32_16x16x32_bf16 v[34:37], v[154:157], v[208:211], v[34:37]
	v_mfma_f32_16x16x32_bf16 v[212:215], v[138:141], v[200:203], v[46:49]
	v_mfma_f32_16x16x32_bf16 v[232:235], v[154:157], v[200:203], v[42:45]
	s_setprio 0
	s_setprio 1
	v_mfma_f32_16x16x32_bf16 v[22:25], v[102:105], v[90:93], v[22:25]
	v_mfma_f32_16x16x32_bf16 v[18:21], v[220:223], v[90:93], v[18:21]
	v_mfma_f32_16x16x32_bf16 v[6:9], v[102:105], v[204:207], v[6:9]
	v_mfma_f32_16x16x32_bf16 v[2:5], v[220:223], v[204:207], v[2:5]
	v_mfma_f32_16x16x32_bf16 v[30:33], v[102:105], v[70:73], v[30:33]
	v_mfma_f32_16x16x32_bf16 v[26:29], v[220:223], v[70:73], v[26:29]
	v_mfma_f32_16x16x32_bf16 v[22:25], v[110:113], v[94:97], v[22:25]
	v_mfma_f32_16x16x32_bf16 v[18:21], v[224:227], v[94:97], v[18:21]
	v_mfma_f32_16x16x32_bf16 v[14:17], v[102:105], v[186:189], v[14:17]
	v_mfma_f32_16x16x32_bf16 v[10:13], v[220:223], v[186:189], v[10:13]
	v_mfma_f32_16x16x32_bf16 v[6:9], v[110:113], v[208:211], v[6:9]
	v_mfma_f32_16x16x32_bf16 v[2:5], v[224:227], v[208:211], v[2:5]
	v_mfma_f32_16x16x32_bf16 v[130:133], v[110:113], v[78:81], v[30:33]
	v_mfma_f32_16x16x32_bf16 v[154:157], v[224:227], v[78:81], v[26:29]
	v_mfma_f32_16x16x32_bf16 v[236:239], v[110:113], v[200:203], v[14:17]
	v_mfma_f32_16x16x32_bf16 v[186:189], v[224:227], v[200:203], v[10:13]
	s_setprio 0
	s_barrier
	s_nop 0
	ds_read_b128 v[10:13], v179
	ds_read_b128 v[14:17], v179 offset:1024
	ds_read_b128 v[200:203], v179 offset:2048
	ds_read_b128 v[204:207], v179 offset:3072
	ds_read_b128 v[26:29], v174 offset:32768
	ds_read_b128 v[30:33], v174 offset:33792
	ds_read_b128 v[42:45], v175 offset:32768
	ds_read_b128 v[46:49], v175 offset:33792
	ds_read_b128 v[208:211], v176 offset:32768
	ds_read_b128 v[220:223], v176 offset:33792
	ds_read_b128 v[224:227], v177 offset:32768
	ds_read_b128 v[240:243], v177 offset:33792
	s_waitcnt vmcnt(2)
	s_barrier
; #define LDA(dst, b, h) for (int m = 0; m < 4; ++m) for (int k = 0; k < 2; ++k) \
;     dst[m][k] = *reinterpret_cast<const bf16x8*>((char*)SA(b, h) + lds_byte(wr * 64 + m * 16 + fr, k * 32 + fq * 8))
; #define LDB(dst, b, h) for (int n = 0; n < 2; ++n) for (int k = 0; k < 2; ++k) \
;     dst[n][k] = *reinterpret_cast<const bf16x8*>((char*)SB(b, h) + lds_byte(wc * 32 + n * 16 + fr, k * 32 + fq * 8))
; #define MMA(ai, bj, At, Bt_) do { __builtin_amdgcn_s_setprio(1); \
;     for (int m = 0; m < 4; ++m) for (int n = 0; n < 2; ++n) for (int k = 0; k < 2; ++k) \
;       acc[ai][bj][m][n] = __builtin_amdgcn_mfma_f32_16x16x32_bf16(Bt_[n][k], At[m][k], acc[ai][bj][m][n], 0, 0, 0); \
;     __builtin_amdgcn_s_setprio(0); } while (0)
; #define WAIT_V(n) asm volatile("s_waitcnt vmcnt(" #n ")" ::: "memory")
; #define WAIT_L(n) asm volatile("s_waitcnt lgkmcnt(" #n ")" ::: "memory")
; #define BAR __builtin_amdgcn_s_barrier()
; template <int EPI> ...
;     ...
;       LDA(At, 0, 1); WAIT_V(4); BAR; WAIT_L(0); MMA(1, 0, At, B0); MMA(1, 1, At, B1); BAR; }
;     { LDB(B0, 1, 0); LDA(At, 1, 0); WAIT_V(2); BAR; WAIT_L(0); MMA(0, 0, At, B0); BAR;
;       LDB(B1, 1, 1); WAIT_V(0); BAR; WAIT_L(0); MMA(0, 1, At, B1); BAR;
;       LDA(At, 1, 1); BAR; WAIT_L(0); MMA(1, 0, At, B0); MMA(1, 1, At, B1); BAR; }
;     if (wr == 0) BAR;
	s_waitcnt lgkmcnt(0)
	s_setprio 1
	s_waitcnt lgkmcnt(0)
	v_mfma_f32_16x16x32_bf16 v[70:73], v[10:13], v[26:29], v[126:129]
	v_mfma_f32_16x16x32_bf16 v[142:145], v[14:17], v[30:33], v[70:73]
	v_mfma_f32_16x16x32_bf16 v[70:73], v[200:203], v[26:29], v[122:125]
	v_mfma_f32_16x16x32_bf16 v[138:141], v[204:207], v[30:33], v[70:73]
	v_mfma_f32_16x16x32_bf16 v[70:73], v[10:13], v[42:45], v[118:121]
	v_mfma_f32_16x16x32_bf16 v[110:113], v[14:17], v[46:49], v[70:73]
	v_mfma_f32_16x16x32_bf16 v[70:73], v[200:203], v[42:45], v[114:117]
	v_mfma_f32_16x16x32_bf16 v[102:105], v[204:207], v[46:49], v[70:73]
	v_mfma_f32_16x16x32_bf16 v[70:73], v[10:13], v[208:211], v[134:137]
	v_mfma_f32_16x16x32_bf16 v[94:97], v[14:17], v[220:223], v[70:73]
	v_mfma_f32_16x16x32_bf16 v[70:73], v[200:203], v[208:211], v[106:109]
	v_mfma_f32_16x16x32_bf16 v[90:93], v[204:207], v[220:223], v[70:73]
	v_mfma_f32_16x16x32_bf16 v[70:73], v[10:13], v[224:227], v[216:219]
	v_mfma_f32_16x16x32_bf16 v[78:81], v[14:17], v[240:243], v[70:73]
	v_mfma_f32_16x16x32_bf16 v[70:73], v[200:203], v[224:227], v[98:101]
	v_mfma_f32_16x16x32_bf16 v[70:73], v[204:207], v[240:243], v[70:73]
	s_setprio 0
	s_barrier
	ds_read_b128 v[118:121], v180
	ds_read_b128 v[122:125], v180 offset:1024
	ds_read_b128 v[126:129], v180 offset:2048
	ds_read_b128 v[216:219], v180 offset:3072
	s_waitcnt vmcnt(0)
	s_barrier
	s_waitcnt lgkmcnt(0)
	s_setprio 1
	s_waitcnt lgkmcnt(0)
	v_mfma_f32_16x16x32_bf16 v[98:101], v[118:121], v[26:29], v[228:231]
	v_mfma_f32_16x16x32_bf16 v[26:29], v[126:129], v[26:29], v[158:161]
	v_mfma_f32_16x16x32_bf16 v[114:117], v[216:219], v[30:33], v[26:29]
	v_mfma_f32_16x16x32_bf16 v[26:29], v[118:121], v[42:45], v[86:89]
	v_mfma_f32_16x16x32_bf16 v[106:109], v[122:125], v[46:49], v[26:29]
	v_mfma_f32_16x16x32_bf16 v[26:29], v[126:129], v[42:45], v[82:85]
	v_mfma_f32_16x16x32_bf16 v[134:137], v[122:125], v[30:33], v[98:101]
	v_mfma_f32_16x16x32_bf16 v[98:101], v[216:219], v[46:49], v[26:29]
	v_mfma_f32_16x16x32_bf16 v[26:29], v[118:121], v[208:211], v[162:165]
	v_mfma_f32_16x16x32_bf16 v[86:89], v[122:125], v[220:223], v[26:29]
	v_mfma_f32_16x16x32_bf16 v[26:29], v[126:129], v[208:211], v[74:77]
	v_mfma_f32_16x16x32_bf16 v[82:85], v[216:219], v[220:223], v[26:29]
	v_mfma_f32_16x16x32_bf16 v[26:29], v[118:121], v[224:227], v[182:185]
	v_mfma_f32_16x16x32_bf16 v[74:77], v[122:125], v[240:243], v[26:29]
	v_mfma_f32_16x16x32_bf16 v[26:29], v[126:129], v[224:227], v[66:69]
	v_mfma_f32_16x16x32_bf16 v[66:69], v[216:219], v[240:243], v[26:29]
	s_setprio 0
	s_barrier
	ds_read_b128 v[158:161], v174 offset:49152
	ds_read_b128 v[162:165], v174 offset:50176
	ds_read_b128 v[182:185], v175 offset:49152
	ds_read_b128 v[208:211], v175 offset:50176
	ds_read_b128 v[220:223], v176 offset:49152
	ds_read_b128 v[224:227], v176 offset:50176
	ds_read_b128 v[228:231], v177 offset:49152
	ds_read_b128 v[240:243], v177 offset:50176
	s_barrier
	s_waitcnt lgkmcnt(0)
	s_setprio 1
	s_waitcnt lgkmcnt(0)
	v_mfma_f32_16x16x32_bf16 v[26:29], v[10:13], v[158:161], v[62:65]
	v_mfma_f32_16x16x32_bf16 v[62:65], v[14:17], v[162:165], v[26:29]
	v_mfma_f32_16x16x32_bf16 v[26:29], v[200:203], v[158:161], v[58:61]
	v_mfma_f32_16x16x32_bf16 v[58:61], v[204:207], v[162:165], v[26:29]
	v_mfma_f32_16x16x32_bf16 v[26:29], v[10:13], v[182:185], v[54:57]
	v_mfma_f32_16x16x32_bf16 v[46:49], v[14:17], v[208:211], v[26:29]
	v_mfma_f32_16x16x32_bf16 v[26:29], v[200:203], v[182:185], v[50:53]
	v_mfma_f32_16x16x32_bf16 v[42:45], v[204:207], v[208:211], v[26:29]
	v_mfma_f32_16x16x32_bf16 v[26:29], v[10:13], v[220:223], v[212:215]
	v_mfma_f32_16x16x32_bf16 v[10:13], v[10:13], v[228:231], v[38:41]
	v_mfma_f32_16x16x32_bf16 v[30:33], v[14:17], v[224:227], v[26:29]
	v_mfma_f32_16x16x32_bf16 v[26:29], v[200:203], v[220:223], v[232:235]
	v_mfma_f32_16x16x32_bf16 v[14:17], v[14:17], v[240:243], v[10:13]
	v_mfma_f32_16x16x32_bf16 v[10:13], v[200:203], v[228:231], v[34:37]
	v_mfma_f32_16x16x32_bf16 v[26:29], v[204:207], v[224:227], v[26:29]
	v_mfma_f32_16x16x32_bf16 v[10:13], v[204:207], v[240:243], v[10:13]
	s_setprio 0
	s_setprio 1
	v_mfma_f32_16x16x32_bf16 v[34:37], v[118:121], v[158:161], v[130:133]
	v_mfma_f32_16x16x32_bf16 v[54:57], v[122:125], v[162:165], v[34:37]
	v_mfma_f32_16x16x32_bf16 v[34:37], v[126:129], v[158:161], v[154:157]
	v_mfma_f32_16x16x32_bf16 v[18:21], v[126:129], v[182:185], v[18:21]
	v_mfma_f32_16x16x32_bf16 v[50:53], v[216:219], v[162:165], v[34:37]
	v_mfma_f32_16x16x32_bf16 v[22:25], v[118:121], v[182:185], v[22:25]
	v_mfma_f32_16x16x32_bf16 v[34:37], v[216:219], v[208:211], v[18:21]
	v_mfma_f32_16x16x32_bf16 v[18:21], v[118:121], v[220:223], v[236:239]
	v_mfma_f32_16x16x32_bf16 v[38:41], v[122:125], v[208:211], v[22:25]
	v_mfma_f32_16x16x32_bf16 v[22:25], v[122:125], v[224:227], v[18:21]
	v_mfma_f32_16x16x32_bf16 v[18:21], v[126:129], v[220:223], v[186:189]
	v_mfma_f32_16x16x32_bf16 v[6:9], v[118:121], v[228:231], v[6:9]
	v_mfma_f32_16x16x32_bf16 v[2:5], v[126:129], v[228:231], v[2:5]
	v_mfma_f32_16x16x32_bf16 v[18:21], v[216:219], v[224:227], v[18:21]
	v_mfma_f32_16x16x32_bf16 v[6:9], v[122:125], v[240:243], v[6:9]
	v_mfma_f32_16x16x32_bf16 v[2:5], v[216:219], v[240:243], v[2:5]
	s_setprio 0
	s_barrier
	s_and_saveexec_b64 s[16:17], s[6:7]
	s_cbranch_execz .LBB0_579
	s_barrier
